# MLA attention unit rewritten by hand: software-pipelined 64-key slots, QK(t+1) MFMAs overlapped with softmax(t) VALU
# speedup vs baseline: 1.0619x; 1.0619x over previous
.LBB0_1885:
	s_or_b64 exec, exec, s[0:1]
	v_readlane_b32 s0, v250, 2
	v_readlane_b32 s1, v250, 3
	v_readlane_b32 s86, v250, 1
	s_andn2_b64 vcc, exec, s[0:1]
	s_waitcnt vmcnt(0) lgkmcnt(0)
	s_barrier
	s_cbranch_vccnz .LBB0_1920
	v_and_b32_e32 v234, 31, v0
	v_bfe_u32 v235, v0, 5, 1
	v_mul_u32_u24_e32 v220, 0xd0, v234
	v_lshl_add_u32 v220, v235, 4, v220
	v_mul_u32_u24_e32 v221, 0x88, v234
	v_lshl_add_u32 v221, v235, 3, v221
	v_add_u32_e32 v221, 0xd000, v221
	v_lshl_or_b32 v1, s87, 5, v234
	v_mul_u32_u24_e32 v237, 0xc0, v1
	v_lshl_add_u32 v237, v235, 4, v237
	v_lshlrev_b32_e32 v236, 10, v1
	v_lshl_add_u32 v236, v235, 3, v236
	v_lshlrev_b32_e32 v226, 4, v0
	v_add_u32_e32 v227, 0x2000, v226
	v_add_u32_e32 v228, 0x4000, v226
	v_lshrrev_b32_e32 v234, 3, v0
	v_and_b32_e32 v235, 7, v0
	v_mul_u32_u24_e32 v229, 0x2200, v234
	v_lshl_add_u32 v229, v235, 4, v229
	v_mul_u32_u24_e32 v225, 0x88, v234
	v_lshl_add_u32 v225, v235, 4, v225
	v_add_u32_e32 v225, 0xd000, v225
	s_mov_b32 s17, 0xaaab
	s_movk_i32 s18, 0xd0
	v_mov_b32_e32 v234, v0
	v_mul_lo_u32 v235, v234, s17
	v_lshrrev_b32_e32 v235, 19, v235
	v_mul_u32_u24_e32 v1, 12, v235
	v_sub_u32_e32 v234, v234, v1
	v_lshrrev_b32_e32 v1, 6, v235
	v_and_b32_e32 v235, 63, v235
	v_mul_u32_u24_e32 v1, 0x3400, v1
	v_mad_u32_u24 v1, v235, s18, v1
	v_lshl_add_u32 v222, v234, 4, v1
	v_add_u32_e32 v234, 512, v0
	v_mul_lo_u32 v235, v234, s17
	v_lshrrev_b32_e32 v235, 19, v235
	v_mul_u32_u24_e32 v1, 12, v235
	v_sub_u32_e32 v234, v234, v1
	v_lshrrev_b32_e32 v1, 6, v235
	v_and_b32_e32 v235, 63, v235
	v_mul_u32_u24_e32 v1, 0x3400, v1
	v_mad_u32_u24 v1, v235, s18, v1
	v_lshl_add_u32 v223, v234, 4, v1
	v_add_u32_e32 v234, 1024, v0
	v_mul_lo_u32 v235, v234, s17
	v_lshrrev_b32_e32 v235, 19, v235
	v_mul_u32_u24_e32 v1, 12, v235
	v_sub_u32_e32 v234, v234, v1
	v_lshrrev_b32_e32 v1, 6, v235
	v_and_b32_e32 v235, 63, v235
	v_mul_u32_u24_e32 v1, 0x3400, v1
	v_mad_u32_u24 v1, v235, s18, v1
	v_lshl_add_u32 v224, v234, 4, v1
.Lmla_unit:
	s_lshr_b32 s17, s2, 4
	s_and_b32 s18, s2, 15
	s_mul_i32 s19, s17, 0xcc000
	s_add_u32 s4, s78, s19
	s_addc_u32 s5, s79, 0
	s_mul_i32 s19, s17, 0x88000
	s_add_u32 s19, s19, 0x1a00000
	s_add_u32 s10, s78, s19
	s_addc_u32 s11, s79, 0
	s_lshl_b32 s19, s17, 12
	s_lshl_b32 s20, s18, 8
	s_add_u32 s19, s19, s20
	s_mul_i32 s19, s19, 0xc0
	s_add_u32 s19, s19, 0x1400000
	s_add_u32 s12, s80, s19
	s_addc_u32 s13, s81, 0
	s_lshr_b32 s19, s17, 3
	s_lshl_b32 s19, s19, 12
	s_add_u32 s19, s19, s20
	s_lshl_b32 s19, s19, 10
	s_and_b32 s21, s17, 7
	s_lshl_b32 s21, s21, 7
	s_add_u32 s19, s19, s21
	s_add_u32 s19, s19, 0x7900000
	s_add_u32 s14, s80, s19
	s_addc_u32 s15, s81, 0
	global_load_dwordx4 v[98:101], v237, s[12:13] offset:0
	global_load_dwordx4 v[102:105], v237, s[12:13] offset:32
	global_load_dwordx4 v[106:109], v237, s[12:13] offset:64
	global_load_dwordx4 v[110:113], v237, s[12:13] offset:96
	global_load_dwordx4 v[114:117], v237, s[12:13] offset:128
	global_load_dwordx4 v[118:121], v237, s[12:13] offset:160
	global_load_dwordx4 v[200:203], v226, s[4:5]
	global_load_dwordx4 v[204:207], v227, s[4:5]
	global_load_dwordx4 v[208:211], v228, s[4:5]
	global_load_dwordx4 v[66:69], v229, s[10:11]
	s_add_u32 s4, s4, 0x6000
	s_addc_u32 s5, s5, 0
	global_load_dwordx4 v[70:73], v226, s[4:5]
	global_load_dwordx4 v[74:77], v227, s[4:5]
	global_load_dwordx4 v[78:81], v228, s[4:5]
	global_load_dwordx4 v[82:85], v229, s[10:11] offset:128
	global_load_dwordx4 v[216:219], v229, s[10:11] offset:256
	s_add_u32 s4, s4, 0x6000
	s_addc_u32 s5, s5, 0
	s_add_u32 s10, s10, 0x180
	s_addc_u32 s11, s11, 0
	v_mov_b32_e32 v2, 0
	v_mov_b32_e32 v3, 0
	v_mov_b32_e32 v4, 0
	v_mov_b32_e32 v5, 0
	v_mov_b32_e32 v6, 0
	v_mov_b32_e32 v7, 0
	v_mov_b32_e32 v8, 0
	v_mov_b32_e32 v9, 0
	v_mov_b32_e32 v10, 0
	v_mov_b32_e32 v11, 0
	v_mov_b32_e32 v12, 0
	v_mov_b32_e32 v13, 0
	v_mov_b32_e32 v14, 0
	v_mov_b32_e32 v15, 0
	v_mov_b32_e32 v16, 0
	v_mov_b32_e32 v17, 0
	v_mov_b32_e32 v18, 0
	v_mov_b32_e32 v19, 0
	v_mov_b32_e32 v20, 0
	v_mov_b32_e32 v21, 0
	v_mov_b32_e32 v22, 0
	v_mov_b32_e32 v23, 0
	v_mov_b32_e32 v24, 0
	v_mov_b32_e32 v25, 0
	v_mov_b32_e32 v26, 0
	v_mov_b32_e32 v27, 0
	v_mov_b32_e32 v28, 0
	v_mov_b32_e32 v29, 0
	v_mov_b32_e32 v30, 0
	v_mov_b32_e32 v31, 0
	v_mov_b32_e32 v32, 0
	v_mov_b32_e32 v33, 0
	v_mov_b32_e32 v122, 0
	v_mov_b32_e32 v123, 0
	v_mov_b32_e32 v124, 0
	v_mov_b32_e32 v125, 0
	v_mov_b32_e32 v126, 0
	v_mov_b32_e32 v127, 0
	v_mov_b32_e32 v128, 0
	v_mov_b32_e32 v129, 0
	v_mov_b32_e32 v130, 0
	v_mov_b32_e32 v131, 0
	v_mov_b32_e32 v132, 0
	v_mov_b32_e32 v133, 0
	v_mov_b32_e32 v134, 0
	v_mov_b32_e32 v135, 0
	v_mov_b32_e32 v136, 0
	v_mov_b32_e32 v137, 0
	v_mov_b32_e32 v230, 0
	v_mov_b32_e32 v231, 0
	v_mov_b32_e32 v232, 0
	s_waitcnt vmcnt(5)
	ds_write_b128 v222, v[200:203]
	ds_write_b128 v223, v[204:207]
	ds_write_b128 v224, v[208:211]
	ds_write_b64 v225, v[66:67]
	ds_write_b64 v225, v[68:69] offset:8
	s_waitcnt vmcnt(1)
	ds_write_b128 v222, v[70:73] offset:26624
	ds_write_b128 v223, v[74:77] offset:26624
	ds_write_b128 v224, v[78:81] offset:26624
	ds_write_b64 v225, v[82:83] offset:8704
	ds_write_b64 v225, v[84:85] offset:8712
	s_waitcnt lgkmcnt(0)
	s_barrier
	ds_read_b128 v[138:141], v220 offset:0
	ds_read_b128 v[142:145], v220 offset:6656
	ds_read_b128 v[146:149], v220 offset:32
	ds_read_b128 v[150:153], v220 offset:6688
	ds_read_b128 v[154:157], v220 offset:64
	ds_read_b128 v[158:161], v220 offset:6720
	ds_read_b128 v[66:69], v220 offset:96
	ds_read_b128 v[70:73], v220 offset:6752
	ds_read_b128 v[74:77], v220 offset:128
	ds_read_b128 v[78:81], v220 offset:6784
	ds_read_b128 v[82:85], v220 offset:160
	ds_read_b128 v[86:89], v220 offset:6816
	s_waitcnt lgkmcnt(11)
	v_mfma_f32_32x32x16_bf16 v[34:49], v[138:141], v[98:101], v[122:137]
	s_waitcnt lgkmcnt(10)
	v_mfma_f32_32x32x16_bf16 v[50:65], v[142:145], v[98:101], v[122:137]
	s_waitcnt lgkmcnt(9)
	v_mfma_f32_32x32x16_bf16 v[34:49], v[146:149], v[102:105], v[34:49]
	s_waitcnt lgkmcnt(8)
	v_mfma_f32_32x32x16_bf16 v[50:65], v[150:153], v[102:105], v[50:65]
	s_waitcnt lgkmcnt(7)
	v_mfma_f32_32x32x16_bf16 v[34:49], v[154:157], v[106:109], v[34:49]
	s_waitcnt lgkmcnt(6)
	v_mfma_f32_32x32x16_bf16 v[50:65], v[158:161], v[106:109], v[50:65]
	s_waitcnt lgkmcnt(5)
	v_mfma_f32_32x32x16_bf16 v[34:49], v[66:69], v[110:113], v[34:49]
	s_waitcnt lgkmcnt(4)
	v_mfma_f32_32x32x16_bf16 v[50:65], v[70:73], v[110:113], v[50:65]
	s_waitcnt lgkmcnt(3)
	v_mfma_f32_32x32x16_bf16 v[34:49], v[74:77], v[114:117], v[34:49]
	s_waitcnt lgkmcnt(2)
	v_mfma_f32_32x32x16_bf16 v[50:65], v[78:81], v[114:117], v[50:65]
	s_waitcnt lgkmcnt(1)
	v_mfma_f32_32x32x16_bf16 v[34:49], v[82:85], v[118:121], v[34:49]
	s_waitcnt lgkmcnt(0)
	v_mfma_f32_32x32x16_bf16 v[50:65], v[86:89], v[118:121], v[50:65]
	s_nop 15
	v_max3_f32 v234, v34, v35, v36
	v_max3_f32 v235, v50, v51, v52
	v_max3_f32 v234, v234, v37, v38
	v_max3_f32 v235, v235, v53, v54
	v_max3_f32 v234, v234, v39, v40
	v_max3_f32 v235, v235, v55, v56
	v_max3_f32 v234, v234, v41, v42
	v_max3_f32 v235, v235, v57, v58
	v_max3_f32 v234, v234, v43, v44
	v_max3_f32 v235, v235, v59, v60
	v_max3_f32 v234, v234, v45, v46
	v_max3_f32 v235, v235, v61, v62
	v_max3_f32 v234, v234, v47, v48
	v_max3_f32 v235, v235, v63, v64
	v_max3_f32 v234, v234, v49, v65
	v_max_f32_e32 v234, v234, v235
	v_mov_b32_e32 v235, v234
	s_nop 1
	v_permlane32_swap_b32_e32 v234, v235
	v_max_f32_e32 v233, v234, v235
	s_nop 15
	v_add_f32_e32 v230, v230, v233
	v_sub_f32_e32 v34, v34, v233
	v_sub_f32_e32 v35, v35, v233
	v_sub_f32_e32 v36, v36, v233
	v_sub_f32_e32 v37, v37, v233
	v_sub_f32_e32 v38, v38, v233
	v_sub_f32_e32 v39, v39, v233
	v_sub_f32_e32 v40, v40, v233
	v_sub_f32_e32 v41, v41, v233
	v_sub_f32_e32 v42, v42, v233
	v_sub_f32_e32 v43, v43, v233
	v_sub_f32_e32 v44, v44, v233
	v_sub_f32_e32 v45, v45, v233
	v_sub_f32_e32 v46, v46, v233
	v_sub_f32_e32 v47, v47, v233
	v_sub_f32_e32 v48, v48, v233
	v_sub_f32_e32 v49, v49, v233
	v_sub_f32_e32 v50, v50, v233
	v_sub_f32_e32 v51, v51, v233
	v_sub_f32_e32 v52, v52, v233
	v_sub_f32_e32 v53, v53, v233
	v_sub_f32_e32 v54, v54, v233
	v_sub_f32_e32 v55, v55, v233
	v_sub_f32_e32 v56, v56, v233
	v_sub_f32_e32 v57, v57, v233
	v_sub_f32_e32 v58, v58, v233
	v_sub_f32_e32 v59, v59, v233
	v_sub_f32_e32 v60, v60, v233
	v_sub_f32_e32 v61, v61, v233
	v_sub_f32_e32 v62, v62, v233
	v_sub_f32_e32 v63, v63, v233
	v_sub_f32_e32 v64, v64, v233
	v_sub_f32_e32 v65, v65, v233
	v_sub_f32_e32 v122, 0, v230
	v_mov_b32_e32 v123, v122
	v_mov_b32_e32 v124, v122
	v_mov_b32_e32 v125, v122
	v_mov_b32_e32 v126, v122
	v_mov_b32_e32 v127, v122
	v_mov_b32_e32 v128, v122
	v_mov_b32_e32 v129, v122
	v_mov_b32_e32 v130, v122
	v_mov_b32_e32 v131, v122
	v_mov_b32_e32 v132, v122
	v_mov_b32_e32 v133, v122
	v_mov_b32_e32 v134, v122
	v_mov_b32_e32 v135, v122
	v_mov_b32_e32 v136, v122
	v_mov_b32_e32 v137, v122
	s_movk_i32 s16, 16
.Lmla_loop:
	global_load_dwordx4 v[200:203], v226, s[4:5]
	global_load_dwordx4 v[204:207], v227, s[4:5]
	global_load_dwordx4 v[208:211], v228, s[4:5]
	s_add_u32 s4, s4, 0x6000
	s_addc_u32 s5, s5, 0
	global_load_dwordx4 v[212:215], v229, s[10:11]
	s_add_u32 s10, s10, 0x80
	s_addc_u32 s11, s11, 0
	ds_read_b128 v[138:141], v220 offset:13312
	ds_read_b128 v[142:145], v220 offset:19968
	ds_read_b128 v[146:149], v220 offset:13344
	ds_read_b128 v[150:153], v220 offset:20000
	ds_read_b128 v[154:157], v220 offset:13376
	ds_read_b128 v[158:161], v220 offset:20032
	v_exp_f32_e32 v34, v34
	v_exp_f32_e32 v35, v35
	v_exp_f32_e32 v36, v36
	v_exp_f32_e32 v37, v37
	s_waitcnt lgkmcnt(5)
	v_mfma_f32_32x32x16_bf16 v[66:81], v[138:141], v[98:101], v[122:137]
	ds_read_b128 v[138:141], v220 offset:13408
	v_add_f32_e32 v231, v231, v34
	v_add_f32_e32 v232, v232, v35
	v_exp_f32_e32 v38, v38
	v_exp_f32_e32 v39, v39
	s_waitcnt lgkmcnt(5)
	v_mfma_f32_32x32x16_bf16 v[82:97], v[142:145], v[98:101], v[122:137]
	ds_read_b128 v[142:145], v220 offset:20064
	v_add_f32_e32 v231, v231, v36
	v_add_f32_e32 v232, v232, v37
	v_exp_f32_e32 v40, v40
	v_exp_f32_e32 v41, v41
	s_waitcnt lgkmcnt(5)
	v_mfma_f32_32x32x16_bf16 v[66:81], v[146:149], v[102:105], v[66:81]
	ds_read_b128 v[146:149], v220 offset:13440
	v_add_f32_e32 v231, v231, v38
	v_add_f32_e32 v232, v232, v39
	v_add_f32_e32 v231, v231, v40
	v_add_f32_e32 v232, v232, v41
	v_cvt_pk_bf16_f32 v34, v34, v35
	v_cvt_pk_bf16_f32 v35, v36, v37
	s_waitcnt lgkmcnt(5)
	v_mfma_f32_32x32x16_bf16 v[82:97], v[150:153], v[102:105], v[82:97]
	ds_read_b128 v[150:153], v220 offset:20096
	v_cvt_pk_bf16_f32 v36, v38, v39
	v_cvt_pk_bf16_f32 v37, v40, v41
	v_exp_f32_e32 v42, v42
	v_exp_f32_e32 v43, v43
	s_waitcnt lgkmcnt(5)
	v_mfma_f32_32x32x16_bf16 v[66:81], v[154:157], v[106:109], v[66:81]
	ds_read_b128 v[154:157], v220 offset:13472
	v_exp_f32_e32 v44, v44
	v_exp_f32_e32 v45, v45
	v_add_f32_e32 v231, v231, v42
	v_add_f32_e32 v232, v232, v43
	s_waitcnt lgkmcnt(5)
	v_mfma_f32_32x32x16_bf16 v[82:97], v[158:161], v[106:109], v[82:97]
	ds_read_b128 v[158:161], v220 offset:20128
	v_exp_f32_e32 v46, v46
	v_exp_f32_e32 v47, v47
	v_add_f32_e32 v231, v231, v44
	v_add_f32_e32 v232, v232, v45
	v_exp_f32_e32 v48, v48
	s_waitcnt lgkmcnt(5)
	v_mfma_f32_32x32x16_bf16 v[66:81], v[138:141], v[110:113], v[66:81]
	ds_read_b64 v[162:163], v221 offset:0
	ds_read_b64 v[164:165], v221 offset:16
	v_exp_f32_e32 v49, v49
	v_add_f32_e32 v231, v231, v46
	v_add_f32_e32 v232, v232, v47
	v_add_f32_e32 v231, v231, v48
	s_waitcnt lgkmcnt(6)
	v_mfma_f32_32x32x16_bf16 v[82:97], v[142:145], v[110:113], v[82:97]
	ds_read_b64 v[166:167], v221 offset:4352
	ds_read_b64 v[168:169], v221 offset:4368
	v_add_f32_e32 v232, v232, v49
	v_cvt_pk_bf16_f32 v42, v42, v43
	v_cvt_pk_bf16_f32 v43, v44, v45
	v_cvt_pk_bf16_f32 v44, v46, v47
	v_cvt_pk_bf16_f32 v45, v48, v49
	v_exp_f32_e32 v50, v50
	s_waitcnt lgkmcnt(7)
	v_mfma_f32_32x32x16_bf16 v[66:81], v[146:149], v[114:117], v[66:81]
	ds_read_b64 v[170:171], v221 offset:32
	ds_read_b64 v[172:173], v221 offset:48
	v_exp_f32_e32 v51, v51
	v_exp_f32_e32 v52, v52
	v_exp_f32_e32 v53, v53
	s_waitcnt lgkmcnt(8)
	v_mfma_f32_32x32x16_bf16 v[82:97], v[150:153], v[114:117], v[82:97]
	ds_read_b64 v[174:175], v221 offset:4384
	ds_read_b64 v[176:177], v221 offset:4400
	v_add_f32_e32 v231, v231, v50
	v_add_f32_e32 v232, v232, v51
	v_exp_f32_e32 v54, v54
	v_exp_f32_e32 v55, v55
	s_waitcnt lgkmcnt(9)
	v_mfma_f32_32x32x16_bf16 v[66:81], v[154:157], v[118:121], v[66:81]
	ds_read_b64 v[180:181], v221 offset:64
	ds_read_b64 v[182:183], v221 offset:80
	v_add_f32_e32 v231, v231, v52
	v_add_f32_e32 v232, v232, v53
	v_exp_f32_e32 v56, v56
	v_exp_f32_e32 v57, v57
	s_waitcnt lgkmcnt(10)
	v_mfma_f32_32x32x16_bf16 v[82:97], v[158:161], v[118:121], v[82:97]
	ds_read_b64 v[184:185], v221 offset:4416
	ds_read_b64 v[186:187], v221 offset:4432
	v_add_f32_e32 v231, v231, v54
	v_add_f32_e32 v232, v232, v55
	v_add_f32_e32 v231, v231, v56
	v_add_f32_e32 v232, v232, v57
	v_cvt_pk_bf16_f32 v50, v50, v51
	v_cvt_pk_bf16_f32 v51, v52, v53
	v_cvt_pk_bf16_f32 v52, v54, v55
	s_waitcnt lgkmcnt(10)
	s_nop 1
	v_mfma_f32_32x32x16_bf16 v[2:17], v[162:165], v[34:37], v[2:17]
	ds_read_b64 v[188:189], v221 offset:96
	ds_read_b64 v[190:191], v221 offset:112
	v_cvt_pk_bf16_f32 v53, v56, v57
	v_exp_f32_e32 v58, v58
	v_exp_f32_e32 v59, v59
	v_exp_f32_e32 v60, v60
	s_waitcnt lgkmcnt(10)
	v_mfma_f32_32x32x16_bf16 v[18:33], v[166:169], v[34:37], v[18:33]
	ds_read_b64 v[192:193], v221 offset:4448
	ds_read_b64 v[194:195], v221 offset:4464
	v_exp_f32_e32 v61, v61
	v_add_f32_e32 v231, v231, v58
	v_add_f32_e32 v232, v232, v59
	v_exp_f32_e32 v62, v62
	s_waitcnt lgkmcnt(10)
	v_mfma_f32_32x32x16_bf16 v[2:17], v[170:173], v[42:45], v[2:17]
	v_exp_f32_e32 v63, v63
	v_add_f32_e32 v231, v231, v60
	v_add_f32_e32 v232, v232, v61
	v_exp_f32_e32 v64, v64
	s_waitcnt lgkmcnt(8)
	v_mfma_f32_32x32x16_bf16 v[18:33], v[174:177], v[42:45], v[18:33]
	s_waitcnt vmcnt(4)
	ds_write_b64 v225, v[216:217] offset:17408
	ds_write_b64 v225, v[218:219] offset:17416
	v_exp_f32_e32 v65, v65
	v_add_f32_e32 v231, v231, v62
	v_add_f32_e32 v232, v232, v63
	v_add_f32_e32 v231, v231, v64
	v_add_f32_e32 v232, v232, v65
	s_waitcnt lgkmcnt(8)
	v_mfma_f32_32x32x16_bf16 v[2:17], v[180:183], v[50:53], v[2:17]
	v_cvt_pk_bf16_f32 v58, v58, v59
	v_cvt_pk_bf16_f32 v59, v60, v61
	v_cvt_pk_bf16_f32 v60, v62, v63
	v_cvt_pk_bf16_f32 v61, v64, v65
	v_max3_f32 v234, v66, v67, v68
	v_max3_f32 v235, v82, v83, v84
	s_waitcnt lgkmcnt(6)
	v_mfma_f32_32x32x16_bf16 v[18:33], v[184:187], v[50:53], v[18:33]
	v_max3_f32 v234, v234, v69, v70
	v_max3_f32 v235, v235, v85, v86
	v_max3_f32 v234, v234, v71, v72
	v_max3_f32 v235, v235, v87, v88
	v_max3_f32 v234, v234, v73, v74
	v_max3_f32 v235, v235, v89, v90
	v_max3_f32 v234, v234, v75, v76
	s_waitcnt lgkmcnt(4)
	v_mfma_f32_32x32x16_bf16 v[2:17], v[188:191], v[58:61], v[2:17]
	v_max3_f32 v235, v235, v91, v92
	v_max3_f32 v234, v234, v77, v78
	v_max3_f32 v235, v235, v93, v94
	v_max3_f32 v234, v234, v79, v80
	v_max3_f32 v235, v235, v95, v96
	v_max3_f32 v234, v234, v81, v97
	s_waitcnt lgkmcnt(2)
	v_mfma_f32_32x32x16_bf16 v[18:33], v[192:195], v[58:61], v[18:33]
	v_max_f32_e32 v234, v234, v235
	v_mov_b32_e32 v235, v234
	s_nop 1
	v_permlane32_swap_b32_e32 v234, v235
	v_max_f32_e32 v233, v234, v235
	v_cmp_lt_f32_e32 vcc, 4.0, v233
	s_cbranch_vccz .Lmla_nr_p0
	s_nop 15
	v_max_f32_e32 v234, 0, v233
	v_exp_f32_e64 v235, -v234
	v_add_f32_e32 v230, v230, v234
	v_sub_f32_e32 v66, v66, v234
	v_sub_f32_e32 v67, v67, v234
	v_sub_f32_e32 v68, v68, v234
	v_sub_f32_e32 v69, v69, v234
	v_sub_f32_e32 v70, v70, v234
	v_sub_f32_e32 v71, v71, v234
	v_sub_f32_e32 v72, v72, v234
	v_sub_f32_e32 v73, v73, v234
	v_sub_f32_e32 v74, v74, v234
	v_sub_f32_e32 v75, v75, v234
	v_sub_f32_e32 v76, v76, v234
	v_sub_f32_e32 v77, v77, v234
	v_sub_f32_e32 v78, v78, v234
	v_sub_f32_e32 v79, v79, v234
	v_sub_f32_e32 v80, v80, v234
	v_sub_f32_e32 v81, v81, v234
	v_sub_f32_e32 v82, v82, v234
	v_sub_f32_e32 v83, v83, v234
	v_sub_f32_e32 v84, v84, v234
	v_sub_f32_e32 v85, v85, v234
	v_sub_f32_e32 v86, v86, v234
	v_sub_f32_e32 v87, v87, v234
	v_sub_f32_e32 v88, v88, v234
	v_sub_f32_e32 v89, v89, v234
	v_sub_f32_e32 v90, v90, v234
	v_sub_f32_e32 v91, v91, v234
	v_sub_f32_e32 v92, v92, v234
	v_sub_f32_e32 v93, v93, v234
	v_sub_f32_e32 v94, v94, v234
	v_sub_f32_e32 v95, v95, v234
	v_sub_f32_e32 v96, v96, v234
	v_sub_f32_e32 v97, v97, v234
	v_mul_f32_e32 v231, v231, v235
	v_mul_f32_e32 v232, v232, v235
	v_mul_f32_e32 v2, v2, v235
	v_mul_f32_e32 v3, v3, v235
	v_mul_f32_e32 v4, v4, v235
	v_mul_f32_e32 v5, v5, v235
	v_mul_f32_e32 v6, v6, v235
	v_mul_f32_e32 v7, v7, v235
	v_mul_f32_e32 v8, v8, v235
	v_mul_f32_e32 v9, v9, v235
	v_mul_f32_e32 v10, v10, v235
	v_mul_f32_e32 v11, v11, v235
	v_mul_f32_e32 v12, v12, v235
	v_mul_f32_e32 v13, v13, v235
	v_mul_f32_e32 v14, v14, v235
	v_mul_f32_e32 v15, v15, v235
	v_mul_f32_e32 v16, v16, v235
	v_mul_f32_e32 v17, v17, v235
	v_mul_f32_e32 v18, v18, v235
	v_mul_f32_e32 v19, v19, v235
	v_mul_f32_e32 v20, v20, v235
	v_mul_f32_e32 v21, v21, v235
	v_mul_f32_e32 v22, v22, v235
	v_mul_f32_e32 v23, v23, v235
	v_mul_f32_e32 v24, v24, v235
	v_mul_f32_e32 v25, v25, v235
	v_mul_f32_e32 v26, v26, v235
	v_mul_f32_e32 v27, v27, v235
	v_mul_f32_e32 v28, v28, v235
	v_mul_f32_e32 v29, v29, v235
	v_mul_f32_e32 v30, v30, v235
	v_mul_f32_e32 v31, v31, v235
	v_mul_f32_e32 v32, v32, v235
	v_mul_f32_e32 v33, v33, v235
	v_sub_f32_e32 v122, 0, v230
	v_mov_b32_e32 v123, v122
	v_mov_b32_e32 v124, v122
	v_mov_b32_e32 v125, v122
	v_mov_b32_e32 v126, v122
	v_mov_b32_e32 v127, v122
	v_mov_b32_e32 v128, v122
	v_mov_b32_e32 v129, v122
	v_mov_b32_e32 v130, v122
	v_mov_b32_e32 v131, v122
	v_mov_b32_e32 v132, v122
	v_mov_b32_e32 v133, v122
	v_mov_b32_e32 v134, v122
	v_mov_b32_e32 v135, v122
	v_mov_b32_e32 v136, v122
	v_mov_b32_e32 v137, v122
.Lmla_nr_p0:
	s_waitcnt lgkmcnt(0)
	s_barrier
	global_load_dwordx4 v[216:219], v229, s[10:11]
	s_add_u32 s10, s10, 0x80
	s_addc_u32 s11, s11, 0
	ds_read_b128 v[138:141], v220 offset:26624
	ds_read_b128 v[142:145], v220 offset:33280
	ds_read_b128 v[146:149], v220 offset:26656
	ds_read_b128 v[150:153], v220 offset:33312
	ds_read_b128 v[154:157], v220 offset:26688
	ds_read_b128 v[158:161], v220 offset:33344
	v_exp_f32_e32 v66, v66
	v_exp_f32_e32 v67, v67
	v_exp_f32_e32 v68, v68
	v_exp_f32_e32 v69, v69
	s_waitcnt lgkmcnt(5)
	v_mfma_f32_32x32x16_bf16 v[34:49], v[138:141], v[98:101], v[122:137]
	ds_read_b128 v[138:141], v220 offset:26720
	v_add_f32_e32 v231, v231, v66
	v_add_f32_e32 v232, v232, v67
	v_exp_f32_e32 v70, v70
	v_exp_f32_e32 v71, v71
	s_waitcnt lgkmcnt(5)
	v_mfma_f32_32x32x16_bf16 v[50:65], v[142:145], v[98:101], v[122:137]
	ds_read_b128 v[142:145], v220 offset:33376
	v_add_f32_e32 v231, v231, v68
	v_add_f32_e32 v232, v232, v69
	v_exp_f32_e32 v72, v72
	v_exp_f32_e32 v73, v73
	s_waitcnt lgkmcnt(5)
	v_mfma_f32_32x32x16_bf16 v[34:49], v[146:149], v[102:105], v[34:49]
	ds_read_b128 v[146:149], v220 offset:26752
	v_add_f32_e32 v231, v231, v70
	v_add_f32_e32 v232, v232, v71
	v_add_f32_e32 v231, v231, v72
	v_add_f32_e32 v232, v232, v73
	v_cvt_pk_bf16_f32 v66, v66, v67
	v_cvt_pk_bf16_f32 v67, v68, v69
	s_waitcnt lgkmcnt(5)
	v_mfma_f32_32x32x16_bf16 v[50:65], v[150:153], v[102:105], v[50:65]
	ds_read_b128 v[150:153], v220 offset:33408
	v_cvt_pk_bf16_f32 v68, v70, v71
	v_cvt_pk_bf16_f32 v69, v72, v73
	v_exp_f32_e32 v74, v74
	v_exp_f32_e32 v75, v75
	s_waitcnt lgkmcnt(5)
	v_mfma_f32_32x32x16_bf16 v[34:49], v[154:157], v[106:109], v[34:49]
	ds_read_b128 v[154:157], v220 offset:26784
	v_exp_f32_e32 v76, v76
	v_exp_f32_e32 v77, v77
	v_add_f32_e32 v231, v231, v74
	v_add_f32_e32 v232, v232, v75
	s_waitcnt lgkmcnt(5)
	v_mfma_f32_32x32x16_bf16 v[50:65], v[158:161], v[106:109], v[50:65]
	ds_read_b128 v[158:161], v220 offset:33440
	v_exp_f32_e32 v78, v78
	v_exp_f32_e32 v79, v79
	v_add_f32_e32 v231, v231, v76
	v_add_f32_e32 v232, v232, v77
	v_exp_f32_e32 v80, v80
	s_waitcnt lgkmcnt(5)
	v_mfma_f32_32x32x16_bf16 v[34:49], v[138:141], v[110:113], v[34:49]
	ds_read_b64 v[162:163], v221 offset:8704
	ds_read_b64 v[164:165], v221 offset:8720
	v_exp_f32_e32 v81, v81
	v_add_f32_e32 v231, v231, v78
	v_add_f32_e32 v232, v232, v79
	v_add_f32_e32 v231, v231, v80
	s_waitcnt lgkmcnt(6)
	v_mfma_f32_32x32x16_bf16 v[50:65], v[142:145], v[110:113], v[50:65]
	ds_read_b64 v[166:167], v221 offset:13056
	ds_read_b64 v[168:169], v221 offset:13072
	v_add_f32_e32 v232, v232, v81
	v_cvt_pk_bf16_f32 v74, v74, v75
	v_cvt_pk_bf16_f32 v75, v76, v77
	v_cvt_pk_bf16_f32 v76, v78, v79
	v_cvt_pk_bf16_f32 v77, v80, v81
	v_exp_f32_e32 v82, v82
	s_waitcnt lgkmcnt(7)
	v_mfma_f32_32x32x16_bf16 v[34:49], v[146:149], v[114:117], v[34:49]
	ds_read_b64 v[170:171], v221 offset:8736
	ds_read_b64 v[172:173], v221 offset:8752
	v_exp_f32_e32 v83, v83
	v_exp_f32_e32 v84, v84
	v_exp_f32_e32 v85, v85
	s_waitcnt lgkmcnt(8)
	v_mfma_f32_32x32x16_bf16 v[50:65], v[150:153], v[114:117], v[50:65]
	ds_read_b64 v[174:175], v221 offset:13088
	ds_read_b64 v[176:177], v221 offset:13104
	v_add_f32_e32 v231, v231, v82
	v_add_f32_e32 v232, v232, v83
	v_exp_f32_e32 v86, v86
	v_exp_f32_e32 v87, v87
	s_waitcnt lgkmcnt(9)
	v_mfma_f32_32x32x16_bf16 v[34:49], v[154:157], v[118:121], v[34:49]
	ds_read_b64 v[180:181], v221 offset:8768
	ds_read_b64 v[182:183], v221 offset:8784
	v_add_f32_e32 v231, v231, v84
	v_add_f32_e32 v232, v232, v85
	v_exp_f32_e32 v88, v88
	v_exp_f32_e32 v89, v89
	s_waitcnt lgkmcnt(10)
	v_mfma_f32_32x32x16_bf16 v[50:65], v[158:161], v[118:121], v[50:65]
	ds_read_b64 v[184:185], v221 offset:13120
	ds_read_b64 v[186:187], v221 offset:13136
	v_add_f32_e32 v231, v231, v86
	v_add_f32_e32 v232, v232, v87
	v_add_f32_e32 v231, v231, v88
	v_add_f32_e32 v232, v232, v89
	v_cvt_pk_bf16_f32 v82, v82, v83
	v_cvt_pk_bf16_f32 v83, v84, v85
	v_cvt_pk_bf16_f32 v84, v86, v87
	s_waitcnt lgkmcnt(10)
	s_nop 1
	v_mfma_f32_32x32x16_bf16 v[2:17], v[162:165], v[66:69], v[2:17]
	ds_read_b64 v[188:189], v221 offset:8800
	ds_read_b64 v[190:191], v221 offset:8816
	v_cvt_pk_bf16_f32 v85, v88, v89
	v_exp_f32_e32 v90, v90
	v_exp_f32_e32 v91, v91
	v_exp_f32_e32 v92, v92
	s_waitcnt lgkmcnt(10)
	v_mfma_f32_32x32x16_bf16 v[18:33], v[166:169], v[66:69], v[18:33]
	ds_read_b64 v[192:193], v221 offset:13152
	ds_read_b64 v[194:195], v221 offset:13168
	v_exp_f32_e32 v93, v93
	v_add_f32_e32 v231, v231, v90
	v_add_f32_e32 v232, v232, v91
	v_exp_f32_e32 v94, v94
	s_waitcnt lgkmcnt(10)
	v_mfma_f32_32x32x16_bf16 v[2:17], v[170:173], v[74:77], v[2:17]
	v_exp_f32_e32 v95, v95
	v_add_f32_e32 v231, v231, v92
	v_add_f32_e32 v232, v232, v93
	v_exp_f32_e32 v96, v96
	s_waitcnt lgkmcnt(8)
	v_mfma_f32_32x32x16_bf16 v[18:33], v[174:177], v[74:77], v[18:33]
	s_waitcnt vmcnt(1)
	ds_write_b128 v222, v[200:203] offset:0
	ds_write_b128 v223, v[204:207] offset:0
	ds_write_b128 v224, v[208:211] offset:0
	ds_write_b64 v225, v[212:213] offset:26112
	ds_write_b64 v225, v[214:215] offset:26120
	v_exp_f32_e32 v97, v97
	v_add_f32_e32 v231, v231, v94
	v_add_f32_e32 v232, v232, v95
	v_add_f32_e32 v231, v231, v96
	v_add_f32_e32 v232, v232, v97
	s_waitcnt lgkmcnt(11)
	v_mfma_f32_32x32x16_bf16 v[2:17], v[180:183], v[82:85], v[2:17]
	v_cvt_pk_bf16_f32 v90, v90, v91
	v_cvt_pk_bf16_f32 v91, v92, v93
	v_cvt_pk_bf16_f32 v92, v94, v95
	v_cvt_pk_bf16_f32 v93, v96, v97
	v_max3_f32 v234, v34, v35, v36
	v_max3_f32 v235, v50, v51, v52
	s_waitcnt lgkmcnt(9)
	v_mfma_f32_32x32x16_bf16 v[18:33], v[184:187], v[82:85], v[18:33]
	v_max3_f32 v234, v234, v37, v38
	v_max3_f32 v235, v235, v53, v54
	v_max3_f32 v234, v234, v39, v40
	v_max3_f32 v235, v235, v55, v56
	v_max3_f32 v234, v234, v41, v42
	v_max3_f32 v235, v235, v57, v58
	v_max3_f32 v234, v234, v43, v44
	s_waitcnt lgkmcnt(7)
	v_mfma_f32_32x32x16_bf16 v[2:17], v[188:191], v[90:93], v[2:17]
	v_max3_f32 v235, v235, v59, v60
	v_max3_f32 v234, v234, v45, v46
	v_max3_f32 v235, v235, v61, v62
	v_max3_f32 v234, v234, v47, v48
	v_max3_f32 v235, v235, v63, v64
	v_max3_f32 v234, v234, v49, v65
	s_waitcnt lgkmcnt(5)
	v_mfma_f32_32x32x16_bf16 v[18:33], v[192:195], v[90:93], v[18:33]
	v_max_f32_e32 v234, v234, v235
	v_mov_b32_e32 v235, v234
	s_nop 1
	v_permlane32_swap_b32_e32 v234, v235
	v_max_f32_e32 v233, v234, v235
	v_cmp_lt_f32_e32 vcc, 4.0, v233
	s_cbranch_vccz .Lmla_nr_p1
	s_nop 15
	v_max_f32_e32 v234, 0, v233
	v_exp_f32_e64 v235, -v234
	v_add_f32_e32 v230, v230, v234
	v_sub_f32_e32 v34, v34, v234
	v_sub_f32_e32 v35, v35, v234
	v_sub_f32_e32 v36, v36, v234
	v_sub_f32_e32 v37, v37, v234
	v_sub_f32_e32 v38, v38, v234
	v_sub_f32_e32 v39, v39, v234
	v_sub_f32_e32 v40, v40, v234
	v_sub_f32_e32 v41, v41, v234
	v_sub_f32_e32 v42, v42, v234
	v_sub_f32_e32 v43, v43, v234
	v_sub_f32_e32 v44, v44, v234
	v_sub_f32_e32 v45, v45, v234
	v_sub_f32_e32 v46, v46, v234
	v_sub_f32_e32 v47, v47, v234
	v_sub_f32_e32 v48, v48, v234
	v_sub_f32_e32 v49, v49, v234
	v_sub_f32_e32 v50, v50, v234
	v_sub_f32_e32 v51, v51, v234
	v_sub_f32_e32 v52, v52, v234
	v_sub_f32_e32 v53, v53, v234
	v_sub_f32_e32 v54, v54, v234
	v_sub_f32_e32 v55, v55, v234
	v_sub_f32_e32 v56, v56, v234
	v_sub_f32_e32 v57, v57, v234
	v_sub_f32_e32 v58, v58, v234
	v_sub_f32_e32 v59, v59, v234
	v_sub_f32_e32 v60, v60, v234
	v_sub_f32_e32 v61, v61, v234
	v_sub_f32_e32 v62, v62, v234
	v_sub_f32_e32 v63, v63, v234
	v_sub_f32_e32 v64, v64, v234
	v_sub_f32_e32 v65, v65, v234
	v_mul_f32_e32 v231, v231, v235
	v_mul_f32_e32 v232, v232, v235
	v_mul_f32_e32 v2, v2, v235
	v_mul_f32_e32 v3, v3, v235
	v_mul_f32_e32 v4, v4, v235
	v_mul_f32_e32 v5, v5, v235
	v_mul_f32_e32 v6, v6, v235
	v_mul_f32_e32 v7, v7, v235
	v_mul_f32_e32 v8, v8, v235
	v_mul_f32_e32 v9, v9, v235
	v_mul_f32_e32 v10, v10, v235
	v_mul_f32_e32 v11, v11, v235
	v_mul_f32_e32 v12, v12, v235
	v_mul_f32_e32 v13, v13, v235
	v_mul_f32_e32 v14, v14, v235
	v_mul_f32_e32 v15, v15, v235
	v_mul_f32_e32 v16, v16, v235
	v_mul_f32_e32 v17, v17, v235
	v_mul_f32_e32 v18, v18, v235
	v_mul_f32_e32 v19, v19, v235
	v_mul_f32_e32 v20, v20, v235
	v_mul_f32_e32 v21, v21, v235
	v_mul_f32_e32 v22, v22, v235
	v_mul_f32_e32 v23, v23, v235
	v_mul_f32_e32 v24, v24, v235
	v_mul_f32_e32 v25, v25, v235
	v_mul_f32_e32 v26, v26, v235
	v_mul_f32_e32 v27, v27, v235
	v_mul_f32_e32 v28, v28, v235
	v_mul_f32_e32 v29, v29, v235
	v_mul_f32_e32 v30, v30, v235
	v_mul_f32_e32 v31, v31, v235
	v_mul_f32_e32 v32, v32, v235
	v_mul_f32_e32 v33, v33, v235
	v_sub_f32_e32 v122, 0, v230
	v_mov_b32_e32 v123, v122
	v_mov_b32_e32 v124, v122
	v_mov_b32_e32 v125, v122
	v_mov_b32_e32 v126, v122
	v_mov_b32_e32 v127, v122
	v_mov_b32_e32 v128, v122
	v_mov_b32_e32 v129, v122
	v_mov_b32_e32 v130, v122
	v_mov_b32_e32 v131, v122
	v_mov_b32_e32 v132, v122
	v_mov_b32_e32 v133, v122
	v_mov_b32_e32 v134, v122
	v_mov_b32_e32 v135, v122
	v_mov_b32_e32 v136, v122
	v_mov_b32_e32 v137, v122
.Lmla_nr_p1:
	s_waitcnt lgkmcnt(0)
	s_barrier
	global_load_dwordx4 v[200:203], v226, s[4:5]
	global_load_dwordx4 v[204:207], v227, s[4:5]
	global_load_dwordx4 v[208:211], v228, s[4:5]
	s_add_u32 s4, s4, 0x6000
	s_addc_u32 s5, s5, 0
	global_load_dwordx4 v[212:215], v229, s[10:11]
	s_add_u32 s10, s10, 0x80
	s_addc_u32 s11, s11, 0
	ds_read_b128 v[138:141], v220 offset:39936
	ds_read_b128 v[142:145], v220 offset:46592
	ds_read_b128 v[146:149], v220 offset:39968
	ds_read_b128 v[150:153], v220 offset:46624
	ds_read_b128 v[154:157], v220 offset:40000
	ds_read_b128 v[158:161], v220 offset:46656
	v_exp_f32_e32 v34, v34
	v_exp_f32_e32 v35, v35
	v_exp_f32_e32 v36, v36
	v_exp_f32_e32 v37, v37
	s_waitcnt lgkmcnt(5)
	v_mfma_f32_32x32x16_bf16 v[66:81], v[138:141], v[98:101], v[122:137]
	ds_read_b128 v[138:141], v220 offset:40032
	v_add_f32_e32 v231, v231, v34
	v_add_f32_e32 v232, v232, v35
	v_exp_f32_e32 v38, v38
	v_exp_f32_e32 v39, v39
	s_waitcnt lgkmcnt(5)
	v_mfma_f32_32x32x16_bf16 v[82:97], v[142:145], v[98:101], v[122:137]
	ds_read_b128 v[142:145], v220 offset:46688
	v_add_f32_e32 v231, v231, v36
	v_add_f32_e32 v232, v232, v37
	v_exp_f32_e32 v40, v40
	v_exp_f32_e32 v41, v41
	s_waitcnt lgkmcnt(5)
	v_mfma_f32_32x32x16_bf16 v[66:81], v[146:149], v[102:105], v[66:81]
	ds_read_b128 v[146:149], v220 offset:40064
	v_add_f32_e32 v231, v231, v38
	v_add_f32_e32 v232, v232, v39
	v_add_f32_e32 v231, v231, v40
	v_add_f32_e32 v232, v232, v41
	v_cvt_pk_bf16_f32 v34, v34, v35
	v_cvt_pk_bf16_f32 v35, v36, v37
	s_waitcnt lgkmcnt(5)
	v_mfma_f32_32x32x16_bf16 v[82:97], v[150:153], v[102:105], v[82:97]
	ds_read_b128 v[150:153], v220 offset:46720
	v_cvt_pk_bf16_f32 v36, v38, v39
	v_cvt_pk_bf16_f32 v37, v40, v41
	v_exp_f32_e32 v42, v42
	v_exp_f32_e32 v43, v43
	s_waitcnt lgkmcnt(5)
	v_mfma_f32_32x32x16_bf16 v[66:81], v[154:157], v[106:109], v[66:81]
	ds_read_b128 v[154:157], v220 offset:40096
	v_exp_f32_e32 v44, v44
	v_exp_f32_e32 v45, v45
	v_add_f32_e32 v231, v231, v42
	v_add_f32_e32 v232, v232, v43
	s_waitcnt lgkmcnt(5)
	v_mfma_f32_32x32x16_bf16 v[82:97], v[158:161], v[106:109], v[82:97]
	ds_read_b128 v[158:161], v220 offset:46752
	v_exp_f32_e32 v46, v46
	v_exp_f32_e32 v47, v47
	v_add_f32_e32 v231, v231, v44
	v_add_f32_e32 v232, v232, v45
	v_exp_f32_e32 v48, v48
	s_waitcnt lgkmcnt(5)
	v_mfma_f32_32x32x16_bf16 v[66:81], v[138:141], v[110:113], v[66:81]
	ds_read_b64 v[162:163], v221 offset:17408
	ds_read_b64 v[164:165], v221 offset:17424
	v_exp_f32_e32 v49, v49
	v_add_f32_e32 v231, v231, v46
	v_add_f32_e32 v232, v232, v47
	v_add_f32_e32 v231, v231, v48
	s_waitcnt lgkmcnt(6)
	v_mfma_f32_32x32x16_bf16 v[82:97], v[142:145], v[110:113], v[82:97]
	ds_read_b64 v[166:167], v221 offset:21760
	ds_read_b64 v[168:169], v221 offset:21776
	v_add_f32_e32 v232, v232, v49
	v_cvt_pk_bf16_f32 v42, v42, v43
	v_cvt_pk_bf16_f32 v43, v44, v45
	v_cvt_pk_bf16_f32 v44, v46, v47
	v_cvt_pk_bf16_f32 v45, v48, v49
	v_exp_f32_e32 v50, v50
	s_waitcnt lgkmcnt(7)
	v_mfma_f32_32x32x16_bf16 v[66:81], v[146:149], v[114:117], v[66:81]
	ds_read_b64 v[170:171], v221 offset:17440
	ds_read_b64 v[172:173], v221 offset:17456
	v_exp_f32_e32 v51, v51
	v_exp_f32_e32 v52, v52
	v_exp_f32_e32 v53, v53
	s_waitcnt lgkmcnt(8)
	v_mfma_f32_32x32x16_bf16 v[82:97], v[150:153], v[114:117], v[82:97]
	ds_read_b64 v[174:175], v221 offset:21792
	ds_read_b64 v[176:177], v221 offset:21808
	v_add_f32_e32 v231, v231, v50
	v_add_f32_e32 v232, v232, v51
	v_exp_f32_e32 v54, v54
	v_exp_f32_e32 v55, v55
	s_waitcnt lgkmcnt(9)
	v_mfma_f32_32x32x16_bf16 v[66:81], v[154:157], v[118:121], v[66:81]
	ds_read_b64 v[180:181], v221 offset:17472
	ds_read_b64 v[182:183], v221 offset:17488
	v_add_f32_e32 v231, v231, v52
	v_add_f32_e32 v232, v232, v53
	v_exp_f32_e32 v56, v56
	v_exp_f32_e32 v57, v57
	s_waitcnt lgkmcnt(10)
	v_mfma_f32_32x32x16_bf16 v[82:97], v[158:161], v[118:121], v[82:97]
	ds_read_b64 v[184:185], v221 offset:21824
	ds_read_b64 v[186:187], v221 offset:21840
	v_add_f32_e32 v231, v231, v54
	v_add_f32_e32 v232, v232, v55
	v_add_f32_e32 v231, v231, v56
	v_add_f32_e32 v232, v232, v57
	v_cvt_pk_bf16_f32 v50, v50, v51
	v_cvt_pk_bf16_f32 v51, v52, v53
	v_cvt_pk_bf16_f32 v52, v54, v55
	s_waitcnt lgkmcnt(10)
	s_nop 1
	v_mfma_f32_32x32x16_bf16 v[2:17], v[162:165], v[34:37], v[2:17]
	ds_read_b64 v[188:189], v221 offset:17504
	ds_read_b64 v[190:191], v221 offset:17520
	v_cvt_pk_bf16_f32 v53, v56, v57
	v_exp_f32_e32 v58, v58
	v_exp_f32_e32 v59, v59
	v_exp_f32_e32 v60, v60
	s_waitcnt lgkmcnt(10)
	v_mfma_f32_32x32x16_bf16 v[18:33], v[166:169], v[34:37], v[18:33]
	ds_read_b64 v[192:193], v221 offset:21856
	ds_read_b64 v[194:195], v221 offset:21872
	v_exp_f32_e32 v61, v61
	v_add_f32_e32 v231, v231, v58
	v_add_f32_e32 v232, v232, v59
	v_exp_f32_e32 v62, v62
	s_waitcnt lgkmcnt(10)
	v_mfma_f32_32x32x16_bf16 v[2:17], v[170:173], v[42:45], v[2:17]
	v_exp_f32_e32 v63, v63
	v_add_f32_e32 v231, v231, v60
	v_add_f32_e32 v232, v232, v61
	v_exp_f32_e32 v64, v64
	s_waitcnt lgkmcnt(8)
	v_mfma_f32_32x32x16_bf16 v[18:33], v[174:177], v[42:45], v[18:33]
	s_waitcnt vmcnt(4)
	ds_write_b64 v225, v[216:217] offset:0
	ds_write_b64 v225, v[218:219] offset:8
	v_exp_f32_e32 v65, v65
	v_add_f32_e32 v231, v231, v62
	v_add_f32_e32 v232, v232, v63
	v_add_f32_e32 v231, v231, v64
	v_add_f32_e32 v232, v232, v65
	s_waitcnt lgkmcnt(8)
	v_mfma_f32_32x32x16_bf16 v[2:17], v[180:183], v[50:53], v[2:17]
	v_cvt_pk_bf16_f32 v58, v58, v59
	v_cvt_pk_bf16_f32 v59, v60, v61
	v_cvt_pk_bf16_f32 v60, v62, v63
	v_cvt_pk_bf16_f32 v61, v64, v65
	v_max3_f32 v234, v66, v67, v68
	v_max3_f32 v235, v82, v83, v84
	s_waitcnt lgkmcnt(6)
	v_mfma_f32_32x32x16_bf16 v[18:33], v[184:187], v[50:53], v[18:33]
	v_max3_f32 v234, v234, v69, v70
	v_max3_f32 v235, v235, v85, v86
	v_max3_f32 v234, v234, v71, v72
	v_max3_f32 v235, v235, v87, v88
	v_max3_f32 v234, v234, v73, v74
	v_max3_f32 v235, v235, v89, v90
	v_max3_f32 v234, v234, v75, v76
	s_waitcnt lgkmcnt(4)
	v_mfma_f32_32x32x16_bf16 v[2:17], v[188:191], v[58:61], v[2:17]
	v_max3_f32 v235, v235, v91, v92
	v_max3_f32 v234, v234, v77, v78
	v_max3_f32 v235, v235, v93, v94
	v_max3_f32 v234, v234, v79, v80
	v_max3_f32 v235, v235, v95, v96
	v_max3_f32 v234, v234, v81, v97
	s_waitcnt lgkmcnt(2)
	v_mfma_f32_32x32x16_bf16 v[18:33], v[192:195], v[58:61], v[18:33]
	v_max_f32_e32 v234, v234, v235
	v_mov_b32_e32 v235, v234
	s_nop 1
	v_permlane32_swap_b32_e32 v234, v235
	v_max_f32_e32 v233, v234, v235
	v_cmp_lt_f32_e32 vcc, 4.0, v233
	s_cbranch_vccz .Lmla_nr_p2
	s_nop 15
	v_max_f32_e32 v234, 0, v233
	v_exp_f32_e64 v235, -v234
	v_add_f32_e32 v230, v230, v234
	v_sub_f32_e32 v66, v66, v234
	v_sub_f32_e32 v67, v67, v234
	v_sub_f32_e32 v68, v68, v234
	v_sub_f32_e32 v69, v69, v234
	v_sub_f32_e32 v70, v70, v234
	v_sub_f32_e32 v71, v71, v234
	v_sub_f32_e32 v72, v72, v234
	v_sub_f32_e32 v73, v73, v234
	v_sub_f32_e32 v74, v74, v234
	v_sub_f32_e32 v75, v75, v234
	v_sub_f32_e32 v76, v76, v234
	v_sub_f32_e32 v77, v77, v234
	v_sub_f32_e32 v78, v78, v234
	v_sub_f32_e32 v79, v79, v234
	v_sub_f32_e32 v80, v80, v234
	v_sub_f32_e32 v81, v81, v234
	v_sub_f32_e32 v82, v82, v234
	v_sub_f32_e32 v83, v83, v234
	v_sub_f32_e32 v84, v84, v234
	v_sub_f32_e32 v85, v85, v234
	v_sub_f32_e32 v86, v86, v234
	v_sub_f32_e32 v87, v87, v234
	v_sub_f32_e32 v88, v88, v234
	v_sub_f32_e32 v89, v89, v234
	v_sub_f32_e32 v90, v90, v234
	v_sub_f32_e32 v91, v91, v234
	v_sub_f32_e32 v92, v92, v234
	v_sub_f32_e32 v93, v93, v234
	v_sub_f32_e32 v94, v94, v234
	v_sub_f32_e32 v95, v95, v234
	v_sub_f32_e32 v96, v96, v234
	v_sub_f32_e32 v97, v97, v234
	v_mul_f32_e32 v231, v231, v235
	v_mul_f32_e32 v232, v232, v235
	v_mul_f32_e32 v2, v2, v235
	v_mul_f32_e32 v3, v3, v235
	v_mul_f32_e32 v4, v4, v235
	v_mul_f32_e32 v5, v5, v235
	v_mul_f32_e32 v6, v6, v235
	v_mul_f32_e32 v7, v7, v235
	v_mul_f32_e32 v8, v8, v235
	v_mul_f32_e32 v9, v9, v235
	v_mul_f32_e32 v10, v10, v235
	v_mul_f32_e32 v11, v11, v235
	v_mul_f32_e32 v12, v12, v235
	v_mul_f32_e32 v13, v13, v235
	v_mul_f32_e32 v14, v14, v235
	v_mul_f32_e32 v15, v15, v235
	v_mul_f32_e32 v16, v16, v235
	v_mul_f32_e32 v17, v17, v235
	v_mul_f32_e32 v18, v18, v235
	v_mul_f32_e32 v19, v19, v235
	v_mul_f32_e32 v20, v20, v235
	v_mul_f32_e32 v21, v21, v235
	v_mul_f32_e32 v22, v22, v235
	v_mul_f32_e32 v23, v23, v235
	v_mul_f32_e32 v24, v24, v235
	v_mul_f32_e32 v25, v25, v235
	v_mul_f32_e32 v26, v26, v235
	v_mul_f32_e32 v27, v27, v235
	v_mul_f32_e32 v28, v28, v235
	v_mul_f32_e32 v29, v29, v235
	v_mul_f32_e32 v30, v30, v235
	v_mul_f32_e32 v31, v31, v235
	v_mul_f32_e32 v32, v32, v235
	v_mul_f32_e32 v33, v33, v235
	v_sub_f32_e32 v122, 0, v230
	v_mov_b32_e32 v123, v122
	v_mov_b32_e32 v124, v122
	v_mov_b32_e32 v125, v122
	v_mov_b32_e32 v126, v122
	v_mov_b32_e32 v127, v122
	v_mov_b32_e32 v128, v122
	v_mov_b32_e32 v129, v122
	v_mov_b32_e32 v130, v122
	v_mov_b32_e32 v131, v122
	v_mov_b32_e32 v132, v122
	v_mov_b32_e32 v133, v122
	v_mov_b32_e32 v134, v122
	v_mov_b32_e32 v135, v122
	v_mov_b32_e32 v136, v122
	v_mov_b32_e32 v137, v122
.Lmla_nr_p2:
	s_waitcnt lgkmcnt(0)
	s_barrier
	global_load_dwordx4 v[216:219], v229, s[10:11]
	s_add_u32 s10, s10, 0x80
	s_addc_u32 s11, s11, 0
	ds_read_b128 v[138:141], v220 offset:0
	ds_read_b128 v[142:145], v220 offset:6656
	ds_read_b128 v[146:149], v220 offset:32
	ds_read_b128 v[150:153], v220 offset:6688
	ds_read_b128 v[154:157], v220 offset:64
	ds_read_b128 v[158:161], v220 offset:6720
	v_exp_f32_e32 v66, v66
	v_exp_f32_e32 v67, v67
	v_exp_f32_e32 v68, v68
	v_exp_f32_e32 v69, v69
	s_waitcnt lgkmcnt(5)
	v_mfma_f32_32x32x16_bf16 v[34:49], v[138:141], v[98:101], v[122:137]
	ds_read_b128 v[138:141], v220 offset:96
	v_add_f32_e32 v231, v231, v66
	v_add_f32_e32 v232, v232, v67
	v_exp_f32_e32 v70, v70
	v_exp_f32_e32 v71, v71
	s_waitcnt lgkmcnt(5)
	v_mfma_f32_32x32x16_bf16 v[50:65], v[142:145], v[98:101], v[122:137]
	ds_read_b128 v[142:145], v220 offset:6752
	v_add_f32_e32 v231, v231, v68
	v_add_f32_e32 v232, v232, v69
	v_exp_f32_e32 v72, v72
	v_exp_f32_e32 v73, v73
	s_waitcnt lgkmcnt(5)
	v_mfma_f32_32x32x16_bf16 v[34:49], v[146:149], v[102:105], v[34:49]
	ds_read_b128 v[146:149], v220 offset:128
	v_add_f32_e32 v231, v231, v70
	v_add_f32_e32 v232, v232, v71
	v_add_f32_e32 v231, v231, v72
	v_add_f32_e32 v232, v232, v73
	v_cvt_pk_bf16_f32 v66, v66, v67
	v_cvt_pk_bf16_f32 v67, v68, v69
	s_waitcnt lgkmcnt(5)
	v_mfma_f32_32x32x16_bf16 v[50:65], v[150:153], v[102:105], v[50:65]
	ds_read_b128 v[150:153], v220 offset:6784
	v_cvt_pk_bf16_f32 v68, v70, v71
	v_cvt_pk_bf16_f32 v69, v72, v73
	v_exp_f32_e32 v74, v74
	v_exp_f32_e32 v75, v75
	s_waitcnt lgkmcnt(5)
	v_mfma_f32_32x32x16_bf16 v[34:49], v[154:157], v[106:109], v[34:49]
	ds_read_b128 v[154:157], v220 offset:160
	v_exp_f32_e32 v76, v76
	v_exp_f32_e32 v77, v77
	v_add_f32_e32 v231, v231, v74
	v_add_f32_e32 v232, v232, v75
	s_waitcnt lgkmcnt(5)
	v_mfma_f32_32x32x16_bf16 v[50:65], v[158:161], v[106:109], v[50:65]
	ds_read_b128 v[158:161], v220 offset:6816
	v_exp_f32_e32 v78, v78
	v_exp_f32_e32 v79, v79
	v_add_f32_e32 v231, v231, v76
	v_add_f32_e32 v232, v232, v77
	v_exp_f32_e32 v80, v80
	s_waitcnt lgkmcnt(5)
	v_mfma_f32_32x32x16_bf16 v[34:49], v[138:141], v[110:113], v[34:49]
	ds_read_b64 v[162:163], v221 offset:26112
	ds_read_b64 v[164:165], v221 offset:26128
	v_exp_f32_e32 v81, v81
	v_add_f32_e32 v231, v231, v78
	v_add_f32_e32 v232, v232, v79
	v_add_f32_e32 v231, v231, v80
	s_waitcnt lgkmcnt(6)
	v_mfma_f32_32x32x16_bf16 v[50:65], v[142:145], v[110:113], v[50:65]
	ds_read_b64 v[166:167], v221 offset:30464
	ds_read_b64 v[168:169], v221 offset:30480
	v_add_f32_e32 v232, v232, v81
	v_cvt_pk_bf16_f32 v74, v74, v75
	v_cvt_pk_bf16_f32 v75, v76, v77
	v_cvt_pk_bf16_f32 v76, v78, v79
	v_cvt_pk_bf16_f32 v77, v80, v81
	v_exp_f32_e32 v82, v82
	s_waitcnt lgkmcnt(7)
	v_mfma_f32_32x32x16_bf16 v[34:49], v[146:149], v[114:117], v[34:49]
	ds_read_b64 v[170:171], v221 offset:26144
	ds_read_b64 v[172:173], v221 offset:26160
	v_exp_f32_e32 v83, v83
	v_exp_f32_e32 v84, v84
	v_exp_f32_e32 v85, v85
	s_waitcnt lgkmcnt(8)
	v_mfma_f32_32x32x16_bf16 v[50:65], v[150:153], v[114:117], v[50:65]
	ds_read_b64 v[174:175], v221 offset:30496
	ds_read_b64 v[176:177], v221 offset:30512
	v_add_f32_e32 v231, v231, v82
	v_add_f32_e32 v232, v232, v83
	v_exp_f32_e32 v86, v86
	v_exp_f32_e32 v87, v87
	s_waitcnt lgkmcnt(9)
	v_mfma_f32_32x32x16_bf16 v[34:49], v[154:157], v[118:121], v[34:49]
	ds_read_b64 v[180:181], v221 offset:26176
	ds_read_b64 v[182:183], v221 offset:26192
	v_add_f32_e32 v231, v231, v84
	v_add_f32_e32 v232, v232, v85
	v_exp_f32_e32 v88, v88
	v_exp_f32_e32 v89, v89
	s_waitcnt lgkmcnt(10)
	v_mfma_f32_32x32x16_bf16 v[50:65], v[158:161], v[118:121], v[50:65]
	ds_read_b64 v[184:185], v221 offset:30528
	ds_read_b64 v[186:187], v221 offset:30544
	v_add_f32_e32 v231, v231, v86
	v_add_f32_e32 v232, v232, v87
	v_add_f32_e32 v231, v231, v88
	v_add_f32_e32 v232, v232, v89
	v_cvt_pk_bf16_f32 v82, v82, v83
	v_cvt_pk_bf16_f32 v83, v84, v85
	v_cvt_pk_bf16_f32 v84, v86, v87
	s_waitcnt lgkmcnt(10)
	s_nop 1
	v_mfma_f32_32x32x16_bf16 v[2:17], v[162:165], v[66:69], v[2:17]
	ds_read_b64 v[188:189], v221 offset:26208
	ds_read_b64 v[190:191], v221 offset:26224
	v_cvt_pk_bf16_f32 v85, v88, v89
	v_exp_f32_e32 v90, v90
	v_exp_f32_e32 v91, v91
	v_exp_f32_e32 v92, v92
	s_waitcnt lgkmcnt(10)
	v_mfma_f32_32x32x16_bf16 v[18:33], v[166:169], v[66:69], v[18:33]
	ds_read_b64 v[192:193], v221 offset:30560
	ds_read_b64 v[194:195], v221 offset:30576
	v_exp_f32_e32 v93, v93
	v_add_f32_e32 v231, v231, v90
	v_add_f32_e32 v232, v232, v91
	v_exp_f32_e32 v94, v94
	s_waitcnt lgkmcnt(10)
	v_mfma_f32_32x32x16_bf16 v[2:17], v[170:173], v[74:77], v[2:17]
	v_exp_f32_e32 v95, v95
	v_add_f32_e32 v231, v231, v92
	v_add_f32_e32 v232, v232, v93
	v_exp_f32_e32 v96, v96
	s_waitcnt lgkmcnt(8)
	v_mfma_f32_32x32x16_bf16 v[18:33], v[174:177], v[74:77], v[18:33]
	s_waitcnt vmcnt(1)
	ds_write_b128 v222, v[200:203] offset:26624
	ds_write_b128 v223, v[204:207] offset:26624
	ds_write_b128 v224, v[208:211] offset:26624
	ds_write_b64 v225, v[212:213] offset:8704
	ds_write_b64 v225, v[214:215] offset:8712
	v_exp_f32_e32 v97, v97
	v_add_f32_e32 v231, v231, v94
	v_add_f32_e32 v232, v232, v95
	v_add_f32_e32 v231, v231, v96
	v_add_f32_e32 v232, v232, v97
	s_waitcnt lgkmcnt(11)
	v_mfma_f32_32x32x16_bf16 v[2:17], v[180:183], v[82:85], v[2:17]
	v_cvt_pk_bf16_f32 v90, v90, v91
	v_cvt_pk_bf16_f32 v91, v92, v93
	v_cvt_pk_bf16_f32 v92, v94, v95
	v_cvt_pk_bf16_f32 v93, v96, v97
	v_max3_f32 v234, v34, v35, v36
	v_max3_f32 v235, v50, v51, v52
	s_waitcnt lgkmcnt(9)
	v_mfma_f32_32x32x16_bf16 v[18:33], v[184:187], v[82:85], v[18:33]
	v_max3_f32 v234, v234, v37, v38
	v_max3_f32 v235, v235, v53, v54
	v_max3_f32 v234, v234, v39, v40
	v_max3_f32 v235, v235, v55, v56
	v_max3_f32 v234, v234, v41, v42
	v_max3_f32 v235, v235, v57, v58
	v_max3_f32 v234, v234, v43, v44
	s_waitcnt lgkmcnt(7)
	v_mfma_f32_32x32x16_bf16 v[2:17], v[188:191], v[90:93], v[2:17]
	v_max3_f32 v235, v235, v59, v60
	v_max3_f32 v234, v234, v45, v46
	v_max3_f32 v235, v235, v61, v62
	v_max3_f32 v234, v234, v47, v48
	v_max3_f32 v235, v235, v63, v64
	v_max3_f32 v234, v234, v49, v65
	s_waitcnt lgkmcnt(5)
	v_mfma_f32_32x32x16_bf16 v[18:33], v[192:195], v[90:93], v[18:33]
	v_max_f32_e32 v234, v234, v235
	v_mov_b32_e32 v235, v234
	s_nop 1
	v_permlane32_swap_b32_e32 v234, v235
	v_max_f32_e32 v233, v234, v235
	v_cmp_lt_f32_e32 vcc, 4.0, v233
	s_cbranch_vccz .Lmla_nr_p3
	s_nop 15
	v_max_f32_e32 v234, 0, v233
	v_exp_f32_e64 v235, -v234
	v_add_f32_e32 v230, v230, v234
	v_sub_f32_e32 v34, v34, v234
	v_sub_f32_e32 v35, v35, v234
	v_sub_f32_e32 v36, v36, v234
	v_sub_f32_e32 v37, v37, v234
	v_sub_f32_e32 v38, v38, v234
	v_sub_f32_e32 v39, v39, v234
	v_sub_f32_e32 v40, v40, v234
	v_sub_f32_e32 v41, v41, v234
	v_sub_f32_e32 v42, v42, v234
	v_sub_f32_e32 v43, v43, v234
	v_sub_f32_e32 v44, v44, v234
	v_sub_f32_e32 v45, v45, v234
	v_sub_f32_e32 v46, v46, v234
	v_sub_f32_e32 v47, v47, v234
	v_sub_f32_e32 v48, v48, v234
	v_sub_f32_e32 v49, v49, v234
	v_sub_f32_e32 v50, v50, v234
	v_sub_f32_e32 v51, v51, v234
	v_sub_f32_e32 v52, v52, v234
	v_sub_f32_e32 v53, v53, v234
	v_sub_f32_e32 v54, v54, v234
	v_sub_f32_e32 v55, v55, v234
	v_sub_f32_e32 v56, v56, v234
	v_sub_f32_e32 v57, v57, v234
	v_sub_f32_e32 v58, v58, v234
	v_sub_f32_e32 v59, v59, v234
	v_sub_f32_e32 v60, v60, v234
	v_sub_f32_e32 v61, v61, v234
	v_sub_f32_e32 v62, v62, v234
	v_sub_f32_e32 v63, v63, v234
	v_sub_f32_e32 v64, v64, v234
	v_sub_f32_e32 v65, v65, v234
	v_mul_f32_e32 v231, v231, v235
	v_mul_f32_e32 v232, v232, v235
	v_mul_f32_e32 v2, v2, v235
	v_mul_f32_e32 v3, v3, v235
	v_mul_f32_e32 v4, v4, v235
	v_mul_f32_e32 v5, v5, v235
	v_mul_f32_e32 v6, v6, v235
	v_mul_f32_e32 v7, v7, v235
	v_mul_f32_e32 v8, v8, v235
	v_mul_f32_e32 v9, v9, v235
	v_mul_f32_e32 v10, v10, v235
	v_mul_f32_e32 v11, v11, v235
	v_mul_f32_e32 v12, v12, v235
	v_mul_f32_e32 v13, v13, v235
	v_mul_f32_e32 v14, v14, v235
	v_mul_f32_e32 v15, v15, v235
	v_mul_f32_e32 v16, v16, v235
	v_mul_f32_e32 v17, v17, v235
	v_mul_f32_e32 v18, v18, v235
	v_mul_f32_e32 v19, v19, v235
	v_mul_f32_e32 v20, v20, v235
	v_mul_f32_e32 v21, v21, v235
	v_mul_f32_e32 v22, v22, v235
	v_mul_f32_e32 v23, v23, v235
	v_mul_f32_e32 v24, v24, v235
	v_mul_f32_e32 v25, v25, v235
	v_mul_f32_e32 v26, v26, v235
	v_mul_f32_e32 v27, v27, v235
	v_mul_f32_e32 v28, v28, v235
	v_mul_f32_e32 v29, v29, v235
	v_mul_f32_e32 v30, v30, v235
	v_mul_f32_e32 v31, v31, v235
	v_mul_f32_e32 v32, v32, v235
	v_mul_f32_e32 v33, v33, v235
	v_sub_f32_e32 v122, 0, v230
	v_mov_b32_e32 v123, v122
	v_mov_b32_e32 v124, v122
	v_mov_b32_e32 v125, v122
	v_mov_b32_e32 v126, v122
	v_mov_b32_e32 v127, v122
	v_mov_b32_e32 v128, v122
	v_mov_b32_e32 v129, v122
	v_mov_b32_e32 v130, v122
	v_mov_b32_e32 v131, v122
	v_mov_b32_e32 v132, v122
	v_mov_b32_e32 v133, v122
	v_mov_b32_e32 v134, v122
	v_mov_b32_e32 v135, v122
	v_mov_b32_e32 v136, v122
	v_mov_b32_e32 v137, v122
.Lmla_nr_p3:
	s_waitcnt lgkmcnt(0)
	s_barrier
	s_add_i32 s16, s16, -1
	s_cmp_lg_u32 s16, 0
	s_cbranch_scc1 .Lmla_loop
	global_load_dwordx4 v[212:215], v229, s[10:11]
	s_add_u32 s10, s10, 0x80
	s_addc_u32 s11, s11, 0
	ds_read_b128 v[138:141], v220 offset:13312
	ds_read_b128 v[142:145], v220 offset:19968
	ds_read_b128 v[146:149], v220 offset:13344
	ds_read_b128 v[150:153], v220 offset:20000
	ds_read_b128 v[154:157], v220 offset:13376
	ds_read_b128 v[158:161], v220 offset:20032
	v_exp_f32_e32 v34, v34
	v_exp_f32_e32 v35, v35
	v_exp_f32_e32 v36, v36
	v_exp_f32_e32 v37, v37
	s_waitcnt lgkmcnt(5)
	v_mfma_f32_32x32x16_bf16 v[66:81], v[138:141], v[98:101], v[122:137]
	ds_read_b128 v[138:141], v220 offset:13408
	v_add_f32_e32 v231, v231, v34
	v_add_f32_e32 v232, v232, v35
	v_exp_f32_e32 v38, v38
	v_exp_f32_e32 v39, v39
	s_waitcnt lgkmcnt(5)
	v_mfma_f32_32x32x16_bf16 v[82:97], v[142:145], v[98:101], v[122:137]
	ds_read_b128 v[142:145], v220 offset:20064
	v_add_f32_e32 v231, v231, v36
	v_add_f32_e32 v232, v232, v37
	v_exp_f32_e32 v40, v40
	v_exp_f32_e32 v41, v41
	s_waitcnt lgkmcnt(5)
	v_mfma_f32_32x32x16_bf16 v[66:81], v[146:149], v[102:105], v[66:81]
	ds_read_b128 v[146:149], v220 offset:13440
	v_add_f32_e32 v231, v231, v38
	v_add_f32_e32 v232, v232, v39
	v_add_f32_e32 v231, v231, v40
	v_add_f32_e32 v232, v232, v41
	v_cvt_pk_bf16_f32 v34, v34, v35
	v_cvt_pk_bf16_f32 v35, v36, v37
	s_waitcnt lgkmcnt(5)
	v_mfma_f32_32x32x16_bf16 v[82:97], v[150:153], v[102:105], v[82:97]
	ds_read_b128 v[150:153], v220 offset:20096
	v_cvt_pk_bf16_f32 v36, v38, v39
	v_cvt_pk_bf16_f32 v37, v40, v41
	v_exp_f32_e32 v42, v42
	v_exp_f32_e32 v43, v43
	s_waitcnt lgkmcnt(5)
	v_mfma_f32_32x32x16_bf16 v[66:81], v[154:157], v[106:109], v[66:81]
	ds_read_b128 v[154:157], v220 offset:13472
	v_exp_f32_e32 v44, v44
	v_exp_f32_e32 v45, v45
	v_add_f32_e32 v231, v231, v42
	v_add_f32_e32 v232, v232, v43
	s_waitcnt lgkmcnt(5)
	v_mfma_f32_32x32x16_bf16 v[82:97], v[158:161], v[106:109], v[82:97]
	ds_read_b128 v[158:161], v220 offset:20128
	v_exp_f32_e32 v46, v46
	v_exp_f32_e32 v47, v47
	v_add_f32_e32 v231, v231, v44
	v_add_f32_e32 v232, v232, v45
	v_exp_f32_e32 v48, v48
	s_waitcnt lgkmcnt(5)
	v_mfma_f32_32x32x16_bf16 v[66:81], v[138:141], v[110:113], v[66:81]
	ds_read_b64 v[162:163], v221 offset:0
	ds_read_b64 v[164:165], v221 offset:16
	v_exp_f32_e32 v49, v49
	v_add_f32_e32 v231, v231, v46
	v_add_f32_e32 v232, v232, v47
	v_add_f32_e32 v231, v231, v48
	s_waitcnt lgkmcnt(6)
	v_mfma_f32_32x32x16_bf16 v[82:97], v[142:145], v[110:113], v[82:97]
	ds_read_b64 v[166:167], v221 offset:4352
	ds_read_b64 v[168:169], v221 offset:4368
	v_add_f32_e32 v232, v232, v49
	v_cvt_pk_bf16_f32 v42, v42, v43
	v_cvt_pk_bf16_f32 v43, v44, v45
	v_cvt_pk_bf16_f32 v44, v46, v47
	v_cvt_pk_bf16_f32 v45, v48, v49
	v_exp_f32_e32 v50, v50
	s_waitcnt lgkmcnt(7)
	v_mfma_f32_32x32x16_bf16 v[66:81], v[146:149], v[114:117], v[66:81]
	ds_read_b64 v[170:171], v221 offset:32
	ds_read_b64 v[172:173], v221 offset:48
	v_exp_f32_e32 v51, v51
	v_exp_f32_e32 v52, v52
	v_exp_f32_e32 v53, v53
	s_waitcnt lgkmcnt(8)
	v_mfma_f32_32x32x16_bf16 v[82:97], v[150:153], v[114:117], v[82:97]
	ds_read_b64 v[174:175], v221 offset:4384
	ds_read_b64 v[176:177], v221 offset:4400
	v_add_f32_e32 v231, v231, v50
	v_add_f32_e32 v232, v232, v51
	v_exp_f32_e32 v54, v54
	v_exp_f32_e32 v55, v55
	s_waitcnt lgkmcnt(9)
	v_mfma_f32_32x32x16_bf16 v[66:81], v[154:157], v[118:121], v[66:81]
	ds_read_b64 v[180:181], v221 offset:64
	ds_read_b64 v[182:183], v221 offset:80
	v_add_f32_e32 v231, v231, v52
	v_add_f32_e32 v232, v232, v53
	v_exp_f32_e32 v56, v56
	v_exp_f32_e32 v57, v57
	s_waitcnt lgkmcnt(10)
	v_mfma_f32_32x32x16_bf16 v[82:97], v[158:161], v[118:121], v[82:97]
	ds_read_b64 v[184:185], v221 offset:4416
	ds_read_b64 v[186:187], v221 offset:4432
	v_add_f32_e32 v231, v231, v54
	v_add_f32_e32 v232, v232, v55
	v_add_f32_e32 v231, v231, v56
	v_add_f32_e32 v232, v232, v57
	v_cvt_pk_bf16_f32 v50, v50, v51
	v_cvt_pk_bf16_f32 v51, v52, v53
	v_cvt_pk_bf16_f32 v52, v54, v55
	s_waitcnt lgkmcnt(10)
	s_nop 1
	v_mfma_f32_32x32x16_bf16 v[2:17], v[162:165], v[34:37], v[2:17]
	ds_read_b64 v[188:189], v221 offset:96
	ds_read_b64 v[190:191], v221 offset:112
	v_cvt_pk_bf16_f32 v53, v56, v57
	v_exp_f32_e32 v58, v58
	v_exp_f32_e32 v59, v59
	v_exp_f32_e32 v60, v60
	s_waitcnt lgkmcnt(10)
	v_mfma_f32_32x32x16_bf16 v[18:33], v[166:169], v[34:37], v[18:33]
	ds_read_b64 v[192:193], v221 offset:4448
	ds_read_b64 v[194:195], v221 offset:4464
	v_exp_f32_e32 v61, v61
	v_add_f32_e32 v231, v231, v58
	v_add_f32_e32 v232, v232, v59
	v_exp_f32_e32 v62, v62
	s_waitcnt lgkmcnt(10)
	v_mfma_f32_32x32x16_bf16 v[2:17], v[170:173], v[42:45], v[2:17]
	v_exp_f32_e32 v63, v63
	v_add_f32_e32 v231, v231, v60
	v_add_f32_e32 v232, v232, v61
	v_exp_f32_e32 v64, v64
	s_waitcnt lgkmcnt(8)
	v_mfma_f32_32x32x16_bf16 v[18:33], v[174:177], v[42:45], v[18:33]
	s_waitcnt vmcnt(1)
	ds_write_b64 v225, v[216:217] offset:17408
	ds_write_b64 v225, v[218:219] offset:17416
	v_exp_f32_e32 v65, v65
	v_add_f32_e32 v231, v231, v62
	v_add_f32_e32 v232, v232, v63
	v_add_f32_e32 v231, v231, v64
	v_add_f32_e32 v232, v232, v65
	s_waitcnt lgkmcnt(8)
	v_mfma_f32_32x32x16_bf16 v[2:17], v[180:183], v[50:53], v[2:17]
	v_cvt_pk_bf16_f32 v58, v58, v59
	v_cvt_pk_bf16_f32 v59, v60, v61
	v_cvt_pk_bf16_f32 v60, v62, v63
	v_cvt_pk_bf16_f32 v61, v64, v65
	v_max3_f32 v234, v66, v67, v68
	v_max3_f32 v235, v82, v83, v84
	s_waitcnt lgkmcnt(6)
	v_mfma_f32_32x32x16_bf16 v[18:33], v[184:187], v[50:53], v[18:33]
	v_max3_f32 v234, v234, v69, v70
	v_max3_f32 v235, v235, v85, v86
	v_max3_f32 v234, v234, v71, v72
	v_max3_f32 v235, v235, v87, v88
	v_max3_f32 v234, v234, v73, v74
	v_max3_f32 v235, v235, v89, v90
	v_max3_f32 v234, v234, v75, v76
	s_waitcnt lgkmcnt(4)
	v_mfma_f32_32x32x16_bf16 v[2:17], v[188:191], v[58:61], v[2:17]
	v_max3_f32 v235, v235, v91, v92
	v_max3_f32 v234, v234, v77, v78
	v_max3_f32 v235, v235, v93, v94
	v_max3_f32 v234, v234, v79, v80
	v_max3_f32 v235, v235, v95, v96
	v_max3_f32 v234, v234, v81, v97
	s_waitcnt lgkmcnt(2)
	v_mfma_f32_32x32x16_bf16 v[18:33], v[192:195], v[58:61], v[18:33]
	v_max_f32_e32 v234, v234, v235
	v_mov_b32_e32 v235, v234
	s_nop 1
	v_permlane32_swap_b32_e32 v234, v235
	v_max_f32_e32 v233, v234, v235
	v_cmp_lt_f32_e32 vcc, 4.0, v233
	s_cbranch_vccz .Lmla_nr_t0
	s_nop 15
	v_max_f32_e32 v234, 0, v233
	v_exp_f32_e64 v235, -v234
	v_add_f32_e32 v230, v230, v234
	v_sub_f32_e32 v66, v66, v234
	v_sub_f32_e32 v67, v67, v234
	v_sub_f32_e32 v68, v68, v234
	v_sub_f32_e32 v69, v69, v234
	v_sub_f32_e32 v70, v70, v234
	v_sub_f32_e32 v71, v71, v234
	v_sub_f32_e32 v72, v72, v234
	v_sub_f32_e32 v73, v73, v234
	v_sub_f32_e32 v74, v74, v234
	v_sub_f32_e32 v75, v75, v234
	v_sub_f32_e32 v76, v76, v234
	v_sub_f32_e32 v77, v77, v234
	v_sub_f32_e32 v78, v78, v234
	v_sub_f32_e32 v79, v79, v234
	v_sub_f32_e32 v80, v80, v234
	v_sub_f32_e32 v81, v81, v234
	v_sub_f32_e32 v82, v82, v234
	v_sub_f32_e32 v83, v83, v234
	v_sub_f32_e32 v84, v84, v234
	v_sub_f32_e32 v85, v85, v234
	v_sub_f32_e32 v86, v86, v234
	v_sub_f32_e32 v87, v87, v234
	v_sub_f32_e32 v88, v88, v234
	v_sub_f32_e32 v89, v89, v234
	v_sub_f32_e32 v90, v90, v234
	v_sub_f32_e32 v91, v91, v234
	v_sub_f32_e32 v92, v92, v234
	v_sub_f32_e32 v93, v93, v234
	v_sub_f32_e32 v94, v94, v234
	v_sub_f32_e32 v95, v95, v234
	v_sub_f32_e32 v96, v96, v234
	v_sub_f32_e32 v97, v97, v234
	v_mul_f32_e32 v231, v231, v235
	v_mul_f32_e32 v232, v232, v235
	v_mul_f32_e32 v2, v2, v235
	v_mul_f32_e32 v3, v3, v235
	v_mul_f32_e32 v4, v4, v235
	v_mul_f32_e32 v5, v5, v235
	v_mul_f32_e32 v6, v6, v235
	v_mul_f32_e32 v7, v7, v235
	v_mul_f32_e32 v8, v8, v235
	v_mul_f32_e32 v9, v9, v235
	v_mul_f32_e32 v10, v10, v235
	v_mul_f32_e32 v11, v11, v235
	v_mul_f32_e32 v12, v12, v235
	v_mul_f32_e32 v13, v13, v235
	v_mul_f32_e32 v14, v14, v235
	v_mul_f32_e32 v15, v15, v235
	v_mul_f32_e32 v16, v16, v235
	v_mul_f32_e32 v17, v17, v235
	v_mul_f32_e32 v18, v18, v235
	v_mul_f32_e32 v19, v19, v235
	v_mul_f32_e32 v20, v20, v235
	v_mul_f32_e32 v21, v21, v235
	v_mul_f32_e32 v22, v22, v235
	v_mul_f32_e32 v23, v23, v235
	v_mul_f32_e32 v24, v24, v235
	v_mul_f32_e32 v25, v25, v235
	v_mul_f32_e32 v26, v26, v235
	v_mul_f32_e32 v27, v27, v235
	v_mul_f32_e32 v28, v28, v235
	v_mul_f32_e32 v29, v29, v235
	v_mul_f32_e32 v30, v30, v235
	v_mul_f32_e32 v31, v31, v235
	v_mul_f32_e32 v32, v32, v235
	v_mul_f32_e32 v33, v33, v235
	v_sub_f32_e32 v122, 0, v230
	v_mov_b32_e32 v123, v122
	v_mov_b32_e32 v124, v122
	v_mov_b32_e32 v125, v122
	v_mov_b32_e32 v126, v122
	v_mov_b32_e32 v127, v122
	v_mov_b32_e32 v128, v122
	v_mov_b32_e32 v129, v122
	v_mov_b32_e32 v130, v122
	v_mov_b32_e32 v131, v122
	v_mov_b32_e32 v132, v122
	v_mov_b32_e32 v133, v122
	v_mov_b32_e32 v134, v122
	v_mov_b32_e32 v135, v122
	v_mov_b32_e32 v136, v122
	v_mov_b32_e32 v137, v122
.Lmla_nr_t0:
	s_waitcnt lgkmcnt(0)
	s_barrier
	ds_read_b128 v[138:141], v220 offset:26624
	ds_read_b128 v[142:145], v220 offset:33280
	ds_read_b128 v[146:149], v220 offset:26656
	ds_read_b128 v[150:153], v220 offset:33312
	ds_read_b128 v[154:157], v220 offset:26688
	ds_read_b128 v[158:161], v220 offset:33344
	v_exp_f32_e32 v66, v66
	v_exp_f32_e32 v67, v67
	v_exp_f32_e32 v68, v68
	v_exp_f32_e32 v69, v69
	s_waitcnt lgkmcnt(5)
	v_mfma_f32_32x32x16_bf16 v[34:49], v[138:141], v[98:101], v[122:137]
	ds_read_b128 v[138:141], v220 offset:26720
	v_add_f32_e32 v231, v231, v66
	v_add_f32_e32 v232, v232, v67
	v_exp_f32_e32 v70, v70
	v_exp_f32_e32 v71, v71
	s_waitcnt lgkmcnt(5)
	v_mfma_f32_32x32x16_bf16 v[50:65], v[142:145], v[98:101], v[122:137]
	ds_read_b128 v[142:145], v220 offset:33376
	v_add_f32_e32 v231, v231, v68
	v_add_f32_e32 v232, v232, v69
	v_exp_f32_e32 v72, v72
	v_exp_f32_e32 v73, v73
	s_waitcnt lgkmcnt(5)
	v_mfma_f32_32x32x16_bf16 v[34:49], v[146:149], v[102:105], v[34:49]
	ds_read_b128 v[146:149], v220 offset:26752
	v_add_f32_e32 v231, v231, v70
	v_add_f32_e32 v232, v232, v71
	v_add_f32_e32 v231, v231, v72
	v_add_f32_e32 v232, v232, v73
	v_cvt_pk_bf16_f32 v66, v66, v67
	v_cvt_pk_bf16_f32 v67, v68, v69
	s_waitcnt lgkmcnt(5)
	v_mfma_f32_32x32x16_bf16 v[50:65], v[150:153], v[102:105], v[50:65]
	ds_read_b128 v[150:153], v220 offset:33408
	v_cvt_pk_bf16_f32 v68, v70, v71
	v_cvt_pk_bf16_f32 v69, v72, v73
	v_exp_f32_e32 v74, v74
	v_exp_f32_e32 v75, v75
	s_waitcnt lgkmcnt(5)
	v_mfma_f32_32x32x16_bf16 v[34:49], v[154:157], v[106:109], v[34:49]
	ds_read_b128 v[154:157], v220 offset:26784
	v_exp_f32_e32 v76, v76
	v_exp_f32_e32 v77, v77
	v_add_f32_e32 v231, v231, v74
	v_add_f32_e32 v232, v232, v75
	s_waitcnt lgkmcnt(5)
	v_mfma_f32_32x32x16_bf16 v[50:65], v[158:161], v[106:109], v[50:65]
	ds_read_b128 v[158:161], v220 offset:33440
	v_exp_f32_e32 v78, v78
	v_exp_f32_e32 v79, v79
	v_add_f32_e32 v231, v231, v76
	v_add_f32_e32 v232, v232, v77
	v_exp_f32_e32 v80, v80
	s_waitcnt lgkmcnt(5)
	v_mfma_f32_32x32x16_bf16 v[34:49], v[138:141], v[110:113], v[34:49]
	ds_read_b64 v[162:163], v221 offset:8704
	ds_read_b64 v[164:165], v221 offset:8720
	v_exp_f32_e32 v81, v81
	v_add_f32_e32 v231, v231, v78
	v_add_f32_e32 v232, v232, v79
	v_add_f32_e32 v231, v231, v80
	s_waitcnt lgkmcnt(6)
	v_mfma_f32_32x32x16_bf16 v[50:65], v[142:145], v[110:113], v[50:65]
	ds_read_b64 v[166:167], v221 offset:13056
	ds_read_b64 v[168:169], v221 offset:13072
	v_add_f32_e32 v232, v232, v81
	v_cvt_pk_bf16_f32 v74, v74, v75
	v_cvt_pk_bf16_f32 v75, v76, v77
	v_cvt_pk_bf16_f32 v76, v78, v79
	v_cvt_pk_bf16_f32 v77, v80, v81
	v_exp_f32_e32 v82, v82
	s_waitcnt lgkmcnt(7)
	v_mfma_f32_32x32x16_bf16 v[34:49], v[146:149], v[114:117], v[34:49]
	ds_read_b64 v[170:171], v221 offset:8736
	ds_read_b64 v[172:173], v221 offset:8752
	v_exp_f32_e32 v83, v83
	v_exp_f32_e32 v84, v84
	v_exp_f32_e32 v85, v85
	s_waitcnt lgkmcnt(8)
	v_mfma_f32_32x32x16_bf16 v[50:65], v[150:153], v[114:117], v[50:65]
	ds_read_b64 v[174:175], v221 offset:13088
	ds_read_b64 v[176:177], v221 offset:13104
	v_add_f32_e32 v231, v231, v82
	v_add_f32_e32 v232, v232, v83
	v_exp_f32_e32 v86, v86
	v_exp_f32_e32 v87, v87
	s_waitcnt lgkmcnt(9)
	v_mfma_f32_32x32x16_bf16 v[34:49], v[154:157], v[118:121], v[34:49]
	ds_read_b64 v[180:181], v221 offset:8768
	ds_read_b64 v[182:183], v221 offset:8784
	v_add_f32_e32 v231, v231, v84
	v_add_f32_e32 v232, v232, v85
	v_exp_f32_e32 v88, v88
	v_exp_f32_e32 v89, v89
	s_waitcnt lgkmcnt(10)
	v_mfma_f32_32x32x16_bf16 v[50:65], v[158:161], v[118:121], v[50:65]
	ds_read_b64 v[184:185], v221 offset:13120
	ds_read_b64 v[186:187], v221 offset:13136
	v_add_f32_e32 v231, v231, v86
	v_add_f32_e32 v232, v232, v87
	v_add_f32_e32 v231, v231, v88
	v_add_f32_e32 v232, v232, v89
	v_cvt_pk_bf16_f32 v82, v82, v83
	v_cvt_pk_bf16_f32 v83, v84, v85
	v_cvt_pk_bf16_f32 v84, v86, v87
	s_waitcnt lgkmcnt(10)
	s_nop 1
	v_mfma_f32_32x32x16_bf16 v[2:17], v[162:165], v[66:69], v[2:17]
	ds_read_b64 v[188:189], v221 offset:8800
	ds_read_b64 v[190:191], v221 offset:8816
	v_cvt_pk_bf16_f32 v85, v88, v89
	v_exp_f32_e32 v90, v90
	v_exp_f32_e32 v91, v91
	v_exp_f32_e32 v92, v92
	s_waitcnt lgkmcnt(10)
	v_mfma_f32_32x32x16_bf16 v[18:33], v[166:169], v[66:69], v[18:33]
	ds_read_b64 v[192:193], v221 offset:13152
	ds_read_b64 v[194:195], v221 offset:13168
	v_exp_f32_e32 v93, v93
	v_add_f32_e32 v231, v231, v90
	v_add_f32_e32 v232, v232, v91
	v_exp_f32_e32 v94, v94
	s_waitcnt lgkmcnt(10)
	v_mfma_f32_32x32x16_bf16 v[2:17], v[170:173], v[74:77], v[2:17]
	v_exp_f32_e32 v95, v95
	v_add_f32_e32 v231, v231, v92
	v_add_f32_e32 v232, v232, v93
	v_exp_f32_e32 v96, v96
	s_waitcnt lgkmcnt(8)
	v_mfma_f32_32x32x16_bf16 v[18:33], v[174:177], v[74:77], v[18:33]
	s_waitcnt vmcnt(0)
	ds_write_b64 v225, v[212:213] offset:26112
	ds_write_b64 v225, v[214:215] offset:26120
	v_exp_f32_e32 v97, v97
	v_add_f32_e32 v231, v231, v94
	v_add_f32_e32 v232, v232, v95
	v_add_f32_e32 v231, v231, v96
	v_add_f32_e32 v232, v232, v97
	s_waitcnt lgkmcnt(8)
	v_mfma_f32_32x32x16_bf16 v[2:17], v[180:183], v[82:85], v[2:17]
	v_cvt_pk_bf16_f32 v90, v90, v91
	v_cvt_pk_bf16_f32 v91, v92, v93
	v_cvt_pk_bf16_f32 v92, v94, v95
	v_cvt_pk_bf16_f32 v93, v96, v97
	v_max3_f32 v234, v34, v35, v36
	v_max3_f32 v235, v50, v51, v52
	s_waitcnt lgkmcnt(6)
	v_mfma_f32_32x32x16_bf16 v[18:33], v[184:187], v[82:85], v[18:33]
	v_max3_f32 v234, v234, v37, v38
	v_max3_f32 v235, v235, v53, v54
	v_max3_f32 v234, v234, v39, v40
	v_max3_f32 v235, v235, v55, v56
	v_max3_f32 v234, v234, v41, v42
	v_max3_f32 v235, v235, v57, v58
	v_max3_f32 v234, v234, v43, v44
	s_waitcnt lgkmcnt(4)
	v_mfma_f32_32x32x16_bf16 v[2:17], v[188:191], v[90:93], v[2:17]
	v_max3_f32 v235, v235, v59, v60
	v_max3_f32 v234, v234, v45, v46
	v_max3_f32 v235, v235, v61, v62
	v_max3_f32 v234, v234, v47, v48
	v_max3_f32 v235, v235, v63, v64
	v_max3_f32 v234, v234, v49, v65
	s_waitcnt lgkmcnt(2)
	v_mfma_f32_32x32x16_bf16 v[18:33], v[192:195], v[90:93], v[18:33]
	v_max_f32_e32 v234, v234, v235
	v_mov_b32_e32 v235, v234
	s_nop 1
	v_permlane32_swap_b32_e32 v234, v235
	v_max_f32_e32 v233, v234, v235
	v_cmp_lt_f32_e32 vcc, 4.0, v233
	s_cbranch_vccz .Lmla_nr_t1
	s_nop 15
	v_max_f32_e32 v234, 0, v233
	v_exp_f32_e64 v235, -v234
	v_add_f32_e32 v230, v230, v234
	v_sub_f32_e32 v34, v34, v234
	v_sub_f32_e32 v35, v35, v234
	v_sub_f32_e32 v36, v36, v234
	v_sub_f32_e32 v37, v37, v234
	v_sub_f32_e32 v38, v38, v234
	v_sub_f32_e32 v39, v39, v234
	v_sub_f32_e32 v40, v40, v234
	v_sub_f32_e32 v41, v41, v234
	v_sub_f32_e32 v42, v42, v234
	v_sub_f32_e32 v43, v43, v234
	v_sub_f32_e32 v44, v44, v234
	v_sub_f32_e32 v45, v45, v234
	v_sub_f32_e32 v46, v46, v234
	v_sub_f32_e32 v47, v47, v234
	v_sub_f32_e32 v48, v48, v234
	v_sub_f32_e32 v49, v49, v234
	v_sub_f32_e32 v50, v50, v234
	v_sub_f32_e32 v51, v51, v234
	v_sub_f32_e32 v52, v52, v234
	v_sub_f32_e32 v53, v53, v234
	v_sub_f32_e32 v54, v54, v234
	v_sub_f32_e32 v55, v55, v234
	v_sub_f32_e32 v56, v56, v234
	v_sub_f32_e32 v57, v57, v234
	v_sub_f32_e32 v58, v58, v234
	v_sub_f32_e32 v59, v59, v234
	v_sub_f32_e32 v60, v60, v234
	v_sub_f32_e32 v61, v61, v234
	v_sub_f32_e32 v62, v62, v234
	v_sub_f32_e32 v63, v63, v234
	v_sub_f32_e32 v64, v64, v234
	v_sub_f32_e32 v65, v65, v234
	v_mul_f32_e32 v231, v231, v235
	v_mul_f32_e32 v232, v232, v235
	v_mul_f32_e32 v2, v2, v235
	v_mul_f32_e32 v3, v3, v235
	v_mul_f32_e32 v4, v4, v235
	v_mul_f32_e32 v5, v5, v235
	v_mul_f32_e32 v6, v6, v235
	v_mul_f32_e32 v7, v7, v235
	v_mul_f32_e32 v8, v8, v235
	v_mul_f32_e32 v9, v9, v235
	v_mul_f32_e32 v10, v10, v235
	v_mul_f32_e32 v11, v11, v235
	v_mul_f32_e32 v12, v12, v235
	v_mul_f32_e32 v13, v13, v235
	v_mul_f32_e32 v14, v14, v235
	v_mul_f32_e32 v15, v15, v235
	v_mul_f32_e32 v16, v16, v235
	v_mul_f32_e32 v17, v17, v235
	v_mul_f32_e32 v18, v18, v235
	v_mul_f32_e32 v19, v19, v235
	v_mul_f32_e32 v20, v20, v235
	v_mul_f32_e32 v21, v21, v235
	v_mul_f32_e32 v22, v22, v235
	v_mul_f32_e32 v23, v23, v235
	v_mul_f32_e32 v24, v24, v235
	v_mul_f32_e32 v25, v25, v235
	v_mul_f32_e32 v26, v26, v235
	v_mul_f32_e32 v27, v27, v235
	v_mul_f32_e32 v28, v28, v235
	v_mul_f32_e32 v29, v29, v235
	v_mul_f32_e32 v30, v30, v235
	v_mul_f32_e32 v31, v31, v235
	v_mul_f32_e32 v32, v32, v235
	v_mul_f32_e32 v33, v33, v235
	v_sub_f32_e32 v122, 0, v230
	v_mov_b32_e32 v123, v122
	v_mov_b32_e32 v124, v122
	v_mov_b32_e32 v125, v122
	v_mov_b32_e32 v126, v122
	v_mov_b32_e32 v127, v122
	v_mov_b32_e32 v128, v122
	v_mov_b32_e32 v129, v122
	v_mov_b32_e32 v130, v122
	v_mov_b32_e32 v131, v122
	v_mov_b32_e32 v132, v122
	v_mov_b32_e32 v133, v122
	v_mov_b32_e32 v134, v122
	v_mov_b32_e32 v135, v122
	v_mov_b32_e32 v136, v122
	v_mov_b32_e32 v137, v122
.Lmla_nr_t1:
	s_waitcnt lgkmcnt(0)
	s_barrier
	global_load_dwordx2 v[200:201], v236, s[14:15] offset:0
	global_load_dwordx2 v[202:203], v236, s[14:15] offset:16
	global_load_dwordx2 v[204:205], v236, s[14:15] offset:32
	global_load_dwordx2 v[206:207], v236, s[14:15] offset:48
	global_load_dwordx2 v[208:209], v236, s[14:15] offset:64
	global_load_dwordx2 v[210:211], v236, s[14:15] offset:80
	global_load_dwordx2 v[212:213], v236, s[14:15] offset:96
	global_load_dwordx2 v[214:215], v236, s[14:15] offset:112
	ds_read_b128 v[138:141], v220 offset:39936
	ds_read_b128 v[142:145], v220 offset:46592
	ds_read_b128 v[146:149], v220 offset:39968
	ds_read_b128 v[150:153], v220 offset:46624
	ds_read_b128 v[154:157], v220 offset:40000
	ds_read_b128 v[158:161], v220 offset:46656
	v_exp_f32_e32 v34, v34
	v_exp_f32_e32 v35, v35
	v_exp_f32_e32 v36, v36
	v_exp_f32_e32 v37, v37
	s_waitcnt lgkmcnt(5)
	v_mfma_f32_32x32x16_bf16 v[66:81], v[138:141], v[98:101], v[122:137]
	ds_read_b128 v[138:141], v220 offset:40032
	v_add_f32_e32 v231, v231, v34
	v_add_f32_e32 v232, v232, v35
	v_exp_f32_e32 v38, v38
	v_exp_f32_e32 v39, v39
	s_waitcnt lgkmcnt(5)
	v_mfma_f32_32x32x16_bf16 v[82:97], v[142:145], v[98:101], v[122:137]
	ds_read_b128 v[142:145], v220 offset:46688
	v_add_f32_e32 v231, v231, v36
	v_add_f32_e32 v232, v232, v37
	v_exp_f32_e32 v40, v40
	v_exp_f32_e32 v41, v41
	s_waitcnt lgkmcnt(5)
	v_mfma_f32_32x32x16_bf16 v[66:81], v[146:149], v[102:105], v[66:81]
	ds_read_b128 v[146:149], v220 offset:40064
	v_add_f32_e32 v231, v231, v38
	v_add_f32_e32 v232, v232, v39
	v_add_f32_e32 v231, v231, v40
	v_add_f32_e32 v232, v232, v41
	v_cvt_pk_bf16_f32 v34, v34, v35
	v_cvt_pk_bf16_f32 v35, v36, v37
	s_waitcnt lgkmcnt(5)
	v_mfma_f32_32x32x16_bf16 v[82:97], v[150:153], v[102:105], v[82:97]
	ds_read_b128 v[150:153], v220 offset:46720
	v_cvt_pk_bf16_f32 v36, v38, v39
	v_cvt_pk_bf16_f32 v37, v40, v41
	v_exp_f32_e32 v42, v42
	v_exp_f32_e32 v43, v43
	s_waitcnt lgkmcnt(5)
	v_mfma_f32_32x32x16_bf16 v[66:81], v[154:157], v[106:109], v[66:81]
	ds_read_b128 v[154:157], v220 offset:40096
	v_exp_f32_e32 v44, v44
	v_exp_f32_e32 v45, v45
	v_add_f32_e32 v231, v231, v42
	v_add_f32_e32 v232, v232, v43
	s_waitcnt lgkmcnt(5)
	v_mfma_f32_32x32x16_bf16 v[82:97], v[158:161], v[106:109], v[82:97]
	ds_read_b128 v[158:161], v220 offset:46752
	v_exp_f32_e32 v46, v46
	v_exp_f32_e32 v47, v47
	v_add_f32_e32 v231, v231, v44
	v_add_f32_e32 v232, v232, v45
	v_exp_f32_e32 v48, v48
	s_waitcnt lgkmcnt(5)
	v_mfma_f32_32x32x16_bf16 v[66:81], v[138:141], v[110:113], v[66:81]
	ds_read_b64 v[162:163], v221 offset:17408
	ds_read_b64 v[164:165], v221 offset:17424
	v_exp_f32_e32 v49, v49
	v_add_f32_e32 v231, v231, v46
	v_add_f32_e32 v232, v232, v47
	v_add_f32_e32 v231, v231, v48
	s_waitcnt lgkmcnt(6)
	v_mfma_f32_32x32x16_bf16 v[82:97], v[142:145], v[110:113], v[82:97]
	ds_read_b64 v[166:167], v221 offset:21760
	ds_read_b64 v[168:169], v221 offset:21776
	v_add_f32_e32 v232, v232, v49
	v_cvt_pk_bf16_f32 v42, v42, v43
	v_cvt_pk_bf16_f32 v43, v44, v45
	v_cvt_pk_bf16_f32 v44, v46, v47
	v_cvt_pk_bf16_f32 v45, v48, v49
	v_exp_f32_e32 v50, v50
	s_waitcnt lgkmcnt(7)
	v_mfma_f32_32x32x16_bf16 v[66:81], v[146:149], v[114:117], v[66:81]
	ds_read_b64 v[170:171], v221 offset:17440
	ds_read_b64 v[172:173], v221 offset:17456
	v_exp_f32_e32 v51, v51
	v_exp_f32_e32 v52, v52
	v_exp_f32_e32 v53, v53
	s_waitcnt lgkmcnt(8)
	v_mfma_f32_32x32x16_bf16 v[82:97], v[150:153], v[114:117], v[82:97]
	ds_read_b64 v[174:175], v221 offset:21792
	ds_read_b64 v[176:177], v221 offset:21808
	v_add_f32_e32 v231, v231, v50
	v_add_f32_e32 v232, v232, v51
	v_exp_f32_e32 v54, v54
	v_exp_f32_e32 v55, v55
	s_waitcnt lgkmcnt(9)
	v_mfma_f32_32x32x16_bf16 v[66:81], v[154:157], v[118:121], v[66:81]
	ds_read_b64 v[180:181], v221 offset:17472
	ds_read_b64 v[182:183], v221 offset:17488
	v_add_f32_e32 v231, v231, v52
	v_add_f32_e32 v232, v232, v53
	v_exp_f32_e32 v56, v56
	v_exp_f32_e32 v57, v57
	s_waitcnt lgkmcnt(10)
	v_mfma_f32_32x32x16_bf16 v[82:97], v[158:161], v[118:121], v[82:97]
	ds_read_b64 v[184:185], v221 offset:21824
	ds_read_b64 v[186:187], v221 offset:21840
	v_add_f32_e32 v231, v231, v54
	v_add_f32_e32 v232, v232, v55
	v_add_f32_e32 v231, v231, v56
	v_add_f32_e32 v232, v232, v57
	v_cvt_pk_bf16_f32 v50, v50, v51
	v_cvt_pk_bf16_f32 v51, v52, v53
	v_cvt_pk_bf16_f32 v52, v54, v55
	s_waitcnt lgkmcnt(10)
	s_nop 1
	v_mfma_f32_32x32x16_bf16 v[2:17], v[162:165], v[34:37], v[2:17]
	ds_read_b64 v[188:189], v221 offset:17504
	ds_read_b64 v[190:191], v221 offset:17520
	v_cvt_pk_bf16_f32 v53, v56, v57
	v_exp_f32_e32 v58, v58
	v_exp_f32_e32 v59, v59
	v_exp_f32_e32 v60, v60
	s_waitcnt lgkmcnt(10)
	v_mfma_f32_32x32x16_bf16 v[18:33], v[166:169], v[34:37], v[18:33]
	ds_read_b64 v[192:193], v221 offset:21856
	ds_read_b64 v[194:195], v221 offset:21872
	v_exp_f32_e32 v61, v61
	v_add_f32_e32 v231, v231, v58
	v_add_f32_e32 v232, v232, v59
	v_exp_f32_e32 v62, v62
	s_waitcnt lgkmcnt(10)
	v_mfma_f32_32x32x16_bf16 v[2:17], v[170:173], v[42:45], v[2:17]
	v_exp_f32_e32 v63, v63
	v_add_f32_e32 v231, v231, v60
	v_add_f32_e32 v232, v232, v61
	v_exp_f32_e32 v64, v64
	s_waitcnt lgkmcnt(8)
	v_mfma_f32_32x32x16_bf16 v[18:33], v[174:177], v[42:45], v[18:33]
	v_exp_f32_e32 v65, v65
	v_add_f32_e32 v231, v231, v62
	v_add_f32_e32 v232, v232, v63
	v_add_f32_e32 v231, v231, v64
	v_add_f32_e32 v232, v232, v65
	s_waitcnt lgkmcnt(6)
	v_mfma_f32_32x32x16_bf16 v[2:17], v[180:183], v[50:53], v[2:17]
	v_cvt_pk_bf16_f32 v58, v58, v59
	v_cvt_pk_bf16_f32 v59, v60, v61
	v_cvt_pk_bf16_f32 v60, v62, v63
	v_cvt_pk_bf16_f32 v61, v64, v65
	v_max3_f32 v234, v66, v67, v68
	v_max3_f32 v235, v82, v83, v84
	s_waitcnt lgkmcnt(4)
	v_mfma_f32_32x32x16_bf16 v[18:33], v[184:187], v[50:53], v[18:33]
	v_max3_f32 v234, v234, v69, v70
	v_max3_f32 v235, v235, v85, v86
	v_max3_f32 v234, v234, v71, v72
	v_max3_f32 v235, v235, v87, v88
	v_max3_f32 v234, v234, v73, v74
	v_max3_f32 v235, v235, v89, v90
	v_max3_f32 v234, v234, v75, v76
	s_waitcnt lgkmcnt(2)
	v_mfma_f32_32x32x16_bf16 v[2:17], v[188:191], v[58:61], v[2:17]
	v_max3_f32 v235, v235, v91, v92
	v_max3_f32 v234, v234, v77, v78
	v_max3_f32 v235, v235, v93, v94
	v_max3_f32 v234, v234, v79, v80
	v_max3_f32 v235, v235, v95, v96
	v_max3_f32 v234, v234, v81, v97
	s_waitcnt lgkmcnt(0)
	v_mfma_f32_32x32x16_bf16 v[18:33], v[192:195], v[58:61], v[18:33]
	v_max_f32_e32 v234, v234, v235
	v_mov_b32_e32 v235, v234
	s_nop 1
	v_permlane32_swap_b32_e32 v234, v235
	v_max_f32_e32 v233, v234, v235
	v_cmp_lt_f32_e32 vcc, 4.0, v233
	s_cbranch_vccz .Lmla_nr_t2
	s_nop 15
	v_max_f32_e32 v234, 0, v233
	v_exp_f32_e64 v235, -v234
	v_add_f32_e32 v230, v230, v234
	v_sub_f32_e32 v66, v66, v234
	v_sub_f32_e32 v67, v67, v234
	v_sub_f32_e32 v68, v68, v234
	v_sub_f32_e32 v69, v69, v234
	v_sub_f32_e32 v70, v70, v234
	v_sub_f32_e32 v71, v71, v234
	v_sub_f32_e32 v72, v72, v234
	v_sub_f32_e32 v73, v73, v234
	v_sub_f32_e32 v74, v74, v234
	v_sub_f32_e32 v75, v75, v234
	v_sub_f32_e32 v76, v76, v234
	v_sub_f32_e32 v77, v77, v234
	v_sub_f32_e32 v78, v78, v234
	v_sub_f32_e32 v79, v79, v234
	v_sub_f32_e32 v80, v80, v234
	v_sub_f32_e32 v81, v81, v234
	v_sub_f32_e32 v82, v82, v234
	v_sub_f32_e32 v83, v83, v234
	v_sub_f32_e32 v84, v84, v234
	v_sub_f32_e32 v85, v85, v234
	v_sub_f32_e32 v86, v86, v234
	v_sub_f32_e32 v87, v87, v234
	v_sub_f32_e32 v88, v88, v234
	v_sub_f32_e32 v89, v89, v234
	v_sub_f32_e32 v90, v90, v234
	v_sub_f32_e32 v91, v91, v234
	v_sub_f32_e32 v92, v92, v234
	v_sub_f32_e32 v93, v93, v234
	v_sub_f32_e32 v94, v94, v234
	v_sub_f32_e32 v95, v95, v234
	v_sub_f32_e32 v96, v96, v234
	v_sub_f32_e32 v97, v97, v234
	v_mul_f32_e32 v231, v231, v235
	v_mul_f32_e32 v232, v232, v235
	v_mul_f32_e32 v2, v2, v235
	v_mul_f32_e32 v3, v3, v235
	v_mul_f32_e32 v4, v4, v235
	v_mul_f32_e32 v5, v5, v235
	v_mul_f32_e32 v6, v6, v235
	v_mul_f32_e32 v7, v7, v235
	v_mul_f32_e32 v8, v8, v235
	v_mul_f32_e32 v9, v9, v235
	v_mul_f32_e32 v10, v10, v235
	v_mul_f32_e32 v11, v11, v235
	v_mul_f32_e32 v12, v12, v235
	v_mul_f32_e32 v13, v13, v235
	v_mul_f32_e32 v14, v14, v235
	v_mul_f32_e32 v15, v15, v235
	v_mul_f32_e32 v16, v16, v235
	v_mul_f32_e32 v17, v17, v235
	v_mul_f32_e32 v18, v18, v235
	v_mul_f32_e32 v19, v19, v235
	v_mul_f32_e32 v20, v20, v235
	v_mul_f32_e32 v21, v21, v235
	v_mul_f32_e32 v22, v22, v235
	v_mul_f32_e32 v23, v23, v235
	v_mul_f32_e32 v24, v24, v235
	v_mul_f32_e32 v25, v25, v235
	v_mul_f32_e32 v26, v26, v235
	v_mul_f32_e32 v27, v27, v235
	v_mul_f32_e32 v28, v28, v235
	v_mul_f32_e32 v29, v29, v235
	v_mul_f32_e32 v30, v30, v235
	v_mul_f32_e32 v31, v31, v235
	v_mul_f32_e32 v32, v32, v235
	v_mul_f32_e32 v33, v33, v235
	v_sub_f32_e32 v122, 0, v230
	v_mov_b32_e32 v123, v122
	v_mov_b32_e32 v124, v122
	v_mov_b32_e32 v125, v122
	v_mov_b32_e32 v126, v122
	v_mov_b32_e32 v127, v122
	v_mov_b32_e32 v128, v122
	v_mov_b32_e32 v129, v122
	v_mov_b32_e32 v130, v122
	v_mov_b32_e32 v131, v122
	v_mov_b32_e32 v132, v122
	v_mov_b32_e32 v133, v122
	v_mov_b32_e32 v134, v122
	v_mov_b32_e32 v135, v122
	v_mov_b32_e32 v136, v122
	v_mov_b32_e32 v137, v122
.Lmla_nr_t2:
	s_waitcnt lgkmcnt(0)
	s_barrier
	ds_read_b64 v[162:163], v221 offset:26112
	ds_read_b64 v[164:165], v221 offset:26128
	ds_read_b64 v[166:167], v221 offset:30464
	ds_read_b64 v[168:169], v221 offset:30480
	ds_read_b64 v[170:171], v221 offset:26144
	ds_read_b64 v[172:173], v221 offset:26160
	v_exp_f32_e32 v66, v66
	v_exp_f32_e32 v67, v67
	v_exp_f32_e32 v68, v68
	v_exp_f32_e32 v69, v69
	v_add_f32_e32 v231, v231, v66
	v_add_f32_e32 v232, v232, v67
	v_exp_f32_e32 v70, v70
	v_exp_f32_e32 v71, v71
	v_add_f32_e32 v231, v231, v68
	v_add_f32_e32 v232, v232, v69
	v_exp_f32_e32 v72, v72
	v_exp_f32_e32 v73, v73
	v_add_f32_e32 v231, v231, v70
	v_add_f32_e32 v232, v232, v71
	v_add_f32_e32 v231, v231, v72
	v_add_f32_e32 v232, v232, v73
	v_cvt_pk_bf16_f32 v66, v66, v67
	v_cvt_pk_bf16_f32 v67, v68, v69
	v_cvt_pk_bf16_f32 v68, v70, v71
	v_cvt_pk_bf16_f32 v69, v72, v73
	s_waitcnt lgkmcnt(4)
	s_nop 1
	v_mfma_f32_32x32x16_bf16 v[2:17], v[162:165], v[66:69], v[2:17]
	ds_read_b64 v[174:175], v221 offset:30496
	ds_read_b64 v[176:177], v221 offset:30512
	s_waitcnt lgkmcnt(4)
	v_mfma_f32_32x32x16_bf16 v[18:33], v[166:169], v[66:69], v[18:33]
	ds_read_b64 v[180:181], v221 offset:26176
	ds_read_b64 v[182:183], v221 offset:26192
	v_exp_f32_e32 v74, v74
	v_exp_f32_e32 v75, v75
	v_exp_f32_e32 v76, v76
	v_exp_f32_e32 v77, v77
	v_add_f32_e32 v231, v231, v74
	v_add_f32_e32 v232, v232, v75
	v_exp_f32_e32 v78, v78
	v_exp_f32_e32 v79, v79
	v_add_f32_e32 v231, v231, v76
	v_add_f32_e32 v232, v232, v77
	v_exp_f32_e32 v80, v80
	v_exp_f32_e32 v81, v81
	v_add_f32_e32 v231, v231, v78
	v_add_f32_e32 v232, v232, v79
	v_add_f32_e32 v231, v231, v80
	v_add_f32_e32 v232, v232, v81
	v_cvt_pk_bf16_f32 v74, v74, v75
	v_cvt_pk_bf16_f32 v75, v76, v77
	v_cvt_pk_bf16_f32 v76, v78, v79
	v_cvt_pk_bf16_f32 v77, v80, v81
	s_waitcnt lgkmcnt(4)
	s_nop 1
	v_mfma_f32_32x32x16_bf16 v[2:17], v[170:173], v[74:77], v[2:17]
	ds_read_b64 v[184:185], v221 offset:30528
	ds_read_b64 v[186:187], v221 offset:30544
	s_waitcnt lgkmcnt(4)
	v_mfma_f32_32x32x16_bf16 v[18:33], v[174:177], v[74:77], v[18:33]
	ds_read_b64 v[188:189], v221 offset:26208
	ds_read_b64 v[190:191], v221 offset:26224
	v_exp_f32_e32 v82, v82
	v_exp_f32_e32 v83, v83
	v_exp_f32_e32 v84, v84
	v_exp_f32_e32 v85, v85
	v_add_f32_e32 v231, v231, v82
	v_add_f32_e32 v232, v232, v83
	v_exp_f32_e32 v86, v86
	v_exp_f32_e32 v87, v87
	v_add_f32_e32 v231, v231, v84
	v_add_f32_e32 v232, v232, v85
	v_exp_f32_e32 v88, v88
	v_exp_f32_e32 v89, v89
	v_add_f32_e32 v231, v231, v86
	v_add_f32_e32 v232, v232, v87
	v_add_f32_e32 v231, v231, v88
	v_add_f32_e32 v232, v232, v89
	v_cvt_pk_bf16_f32 v82, v82, v83
	v_cvt_pk_bf16_f32 v83, v84, v85
	v_cvt_pk_bf16_f32 v84, v86, v87
	v_cvt_pk_bf16_f32 v85, v88, v89
	s_waitcnt lgkmcnt(4)
	s_nop 1
	v_mfma_f32_32x32x16_bf16 v[2:17], v[180:183], v[82:85], v[2:17]
	ds_read_b64 v[192:193], v221 offset:30560
	ds_read_b64 v[194:195], v221 offset:30576
	s_waitcnt lgkmcnt(4)
	v_mfma_f32_32x32x16_bf16 v[18:33], v[184:187], v[82:85], v[18:33]
	v_exp_f32_e32 v90, v90
	v_exp_f32_e32 v91, v91
	v_exp_f32_e32 v92, v92
	v_exp_f32_e32 v93, v93
	v_add_f32_e32 v231, v231, v90
	v_add_f32_e32 v232, v232, v91
	v_exp_f32_e32 v94, v94
	v_exp_f32_e32 v95, v95
	v_add_f32_e32 v231, v231, v92
	v_add_f32_e32 v232, v232, v93
	v_exp_f32_e32 v96, v96
	v_exp_f32_e32 v97, v97
	v_add_f32_e32 v231, v231, v94
	v_add_f32_e32 v232, v232, v95
	v_add_f32_e32 v231, v231, v96
	v_add_f32_e32 v232, v232, v97
	v_cvt_pk_bf16_f32 v90, v90, v91
	v_cvt_pk_bf16_f32 v91, v92, v93
	v_cvt_pk_bf16_f32 v92, v94, v95
	v_cvt_pk_bf16_f32 v93, v96, v97
	s_waitcnt lgkmcnt(2)
	s_nop 1
	v_mfma_f32_32x32x16_bf16 v[2:17], v[188:191], v[90:93], v[2:17]
	s_waitcnt lgkmcnt(0)
	v_mfma_f32_32x32x16_bf16 v[18:33], v[192:195], v[90:93], v[18:33]
	s_waitcnt lgkmcnt(0)
	s_barrier
	v_add_f32_e32 v231, v231, v232
	v_mov_b32_e32 v235, v231
	s_nop 1
	v_permlane32_swap_b32_e32 v231, v235
	v_add_f32_e32 v234, v231, v235
	v_div_scale_f32 v235, s[22:23], v234, v234, 1.0
	v_rcp_f32_e32 v179, v235
	v_div_scale_f32 v196, vcc, 1.0, v234, 1.0
	v_fma_f32 v197, -v235, v179, 1.0
	v_fmac_f32_e32 v179, v197, v179
	v_mul_f32_e32 v197, v196, v179
	v_fma_f32 v199, -v235, v197, v196
	v_fmac_f32_e32 v197, v199, v179
	v_fma_f32 v235, -v235, v197, v196
	v_div_fmas_f32 v235, v235, v179, v197
	v_div_fixup_f32 v234, v235, v234, 1.0
	s_nop 15
	v_mul_f32_e32 v2, v2, v234
	v_mul_f32_e32 v3, v3, v234
	v_mul_f32_e32 v4, v4, v234
	v_mul_f32_e32 v5, v5, v234
	v_mul_f32_e32 v6, v6, v234
	v_mul_f32_e32 v7, v7, v234
	v_mul_f32_e32 v8, v8, v234
	v_mul_f32_e32 v9, v9, v234
	v_mul_f32_e32 v10, v10, v234
	v_mul_f32_e32 v11, v11, v234
	v_mul_f32_e32 v12, v12, v234
	v_mul_f32_e32 v13, v13, v234
	v_mul_f32_e32 v14, v14, v234
	v_mul_f32_e32 v15, v15, v234
	v_mul_f32_e32 v16, v16, v234
	v_mul_f32_e32 v17, v17, v234
	v_mul_f32_e32 v18, v18, v234
	v_mul_f32_e32 v19, v19, v234
	v_mul_f32_e32 v20, v20, v234
	v_mul_f32_e32 v21, v21, v234
	v_mul_f32_e32 v22, v22, v234
	v_mul_f32_e32 v23, v23, v234
	v_mul_f32_e32 v24, v24, v234
	v_mul_f32_e32 v25, v25, v234
	v_mul_f32_e32 v26, v26, v234
	v_mul_f32_e32 v27, v27, v234
	v_mul_f32_e32 v28, v28, v234
	v_mul_f32_e32 v29, v29, v234
	v_mul_f32_e32 v30, v30, v234
	v_mul_f32_e32 v31, v31, v234
	v_mul_f32_e32 v32, v32, v234
	v_mul_f32_e32 v33, v33, v234
	s_waitcnt vmcnt(0)
	v_lshlrev_b32_e32 v179, 16, v200
	v_and_b32_e32 v196, 0xffff0000, v200
	v_lshlrev_b32_e32 v197, 16, v201
	v_and_b32_e32 v199, 0xffff0000, v201
	v_mul_f32_e32 v2, v2, v179
	v_mul_f32_e32 v3, v3, v196
	v_mul_f32_e32 v4, v4, v197
	v_mul_f32_e32 v5, v5, v199
	v_cvt_pk_bf16_f32 v200, v2, v3
	v_cvt_pk_bf16_f32 v201, v4, v5
	global_store_dwordx2 v236, v[200:201], s[14:15] offset:0
	v_lshlrev_b32_e32 v179, 16, v202
	v_and_b32_e32 v196, 0xffff0000, v202
	v_lshlrev_b32_e32 v197, 16, v203
	v_and_b32_e32 v199, 0xffff0000, v203
	v_mul_f32_e32 v6, v6, v179
	v_mul_f32_e32 v7, v7, v196
	v_mul_f32_e32 v8, v8, v197
	v_mul_f32_e32 v9, v9, v199
	v_cvt_pk_bf16_f32 v202, v6, v7
	v_cvt_pk_bf16_f32 v203, v8, v9
	global_store_dwordx2 v236, v[202:203], s[14:15] offset:16
	v_lshlrev_b32_e32 v179, 16, v204
	v_and_b32_e32 v196, 0xffff0000, v204
	v_lshlrev_b32_e32 v197, 16, v205
	v_and_b32_e32 v199, 0xffff0000, v205
	v_mul_f32_e32 v10, v10, v179
	v_mul_f32_e32 v11, v11, v196
	v_mul_f32_e32 v12, v12, v197
	v_mul_f32_e32 v13, v13, v199
	v_cvt_pk_bf16_f32 v204, v10, v11
	v_cvt_pk_bf16_f32 v205, v12, v13
	global_store_dwordx2 v236, v[204:205], s[14:15] offset:32
	v_lshlrev_b32_e32 v179, 16, v206
	v_and_b32_e32 v196, 0xffff0000, v206
	v_lshlrev_b32_e32 v197, 16, v207
	v_and_b32_e32 v199, 0xffff0000, v207
	v_mul_f32_e32 v14, v14, v179
	v_mul_f32_e32 v15, v15, v196
	v_mul_f32_e32 v16, v16, v197
	v_mul_f32_e32 v17, v17, v199
	v_cvt_pk_bf16_f32 v206, v14, v15
	v_cvt_pk_bf16_f32 v207, v16, v17
	global_store_dwordx2 v236, v[206:207], s[14:15] offset:48
	v_lshlrev_b32_e32 v179, 16, v208
	v_and_b32_e32 v196, 0xffff0000, v208
	v_lshlrev_b32_e32 v197, 16, v209
	v_and_b32_e32 v199, 0xffff0000, v209
	v_mul_f32_e32 v18, v18, v179
	v_mul_f32_e32 v19, v19, v196
	v_mul_f32_e32 v20, v20, v197
	v_mul_f32_e32 v21, v21, v199
	v_cvt_pk_bf16_f32 v208, v18, v19
	v_cvt_pk_bf16_f32 v209, v20, v21
	global_store_dwordx2 v236, v[208:209], s[14:15] offset:64
	v_lshlrev_b32_e32 v179, 16, v210
	v_and_b32_e32 v196, 0xffff0000, v210
	v_lshlrev_b32_e32 v197, 16, v211
	v_and_b32_e32 v199, 0xffff0000, v211
	v_mul_f32_e32 v22, v22, v179
	v_mul_f32_e32 v23, v23, v196
	v_mul_f32_e32 v24, v24, v197
	v_mul_f32_e32 v25, v25, v199
	v_cvt_pk_bf16_f32 v210, v22, v23
	v_cvt_pk_bf16_f32 v211, v24, v25
	global_store_dwordx2 v236, v[210:211], s[14:15] offset:80
	v_lshlrev_b32_e32 v179, 16, v212
	v_and_b32_e32 v196, 0xffff0000, v212
	v_lshlrev_b32_e32 v197, 16, v213
	v_and_b32_e32 v199, 0xffff0000, v213
	v_mul_f32_e32 v26, v26, v179
	v_mul_f32_e32 v27, v27, v196
	v_mul_f32_e32 v28, v28, v197
	v_mul_f32_e32 v29, v29, v199
	v_cvt_pk_bf16_f32 v212, v26, v27
	v_cvt_pk_bf16_f32 v213, v28, v29
	global_store_dwordx2 v236, v[212:213], s[14:15] offset:96
	v_lshlrev_b32_e32 v179, 16, v214
	v_and_b32_e32 v196, 0xffff0000, v214
	v_lshlrev_b32_e32 v197, 16, v215
	v_and_b32_e32 v199, 0xffff0000, v215
	v_mul_f32_e32 v30, v30, v179
	v_mul_f32_e32 v31, v31, v196
	v_mul_f32_e32 v32, v32, v197
	v_mul_f32_e32 v33, v33, v199
	v_cvt_pk_bf16_f32 v214, v30, v31
	v_cvt_pk_bf16_f32 v215, v32, v33
	global_store_dwordx2 v236, v[214:215], s[14:15] offset:112
	s_add_i32 s2, s2, s88
	s_cmpk_lt_i32 s2, 0x200
	s_cbranch_scc1 .Lmla_unit
